# peel first K-iteration of each non-first GEMM tile with relaxed vmcnt(24) so epilogue stores need not drain before MFMA starts; plus EpiY load hoist
# speedup vs baseline: 1.0230x; 1.0117x over previous
.LBB0_80:
	s_add_u32 s2, s14, 0x100
	v_mov_b32_e32 v0, 0
	s_addc_u32 s8, s15, 0
	s_mov_b32 s9, -2
	v_mov_b32_e32 v1, v0
	v_mov_b32_e32 v2, v0
	v_mov_b32_e32 v3, v0
	v_mov_b32_e32 v6, v0
	s_waitcnt lgkmcnt(0)
	v_mov_b32_e32 v7, v0
	v_mov_b32_e32 v8, v0
	v_mov_b32_e32 v9, v0
	v_mov_b32_e32 v18, v0
	v_mov_b32_e32 v19, v0
	v_mov_b32_e32 v20, v0
	v_mov_b32_e32 v21, v0
	v_mov_b32_e32 v22, v0
	v_mov_b32_e32 v23, v0
	v_mov_b32_e32 v24, v0
	v_mov_b32_e32 v25, v0
	v_mov_b32_e32 v34, v0
	v_mov_b32_e32 v35, v0
	v_mov_b32_e32 v36, v0
	v_mov_b32_e32 v37, v0
	v_mov_b32_e32 v38, v0
	v_mov_b32_e32 v39, v0
	v_mov_b32_e32 v40, v0
	v_mov_b32_e32 v41, v0
	v_mov_b32_e32 v50, v0
	v_mov_b32_e32 v51, v0
	v_mov_b32_e32 v52, v0
	v_mov_b32_e32 v53, v0
	v_mov_b32_e32 v54, v0
	v_mov_b32_e32 v55, v0
	v_mov_b32_e32 v56, v0
	v_mov_b32_e32 v57, v0
	v_mov_b32_e32 v10, v0
	v_mov_b32_e32 v11, v0
	v_mov_b32_e32 v12, v0
	v_mov_b32_e32 v13, v0
	v_mov_b32_e32 v14, v0
	v_mov_b32_e32 v15, v0
	v_mov_b32_e32 v16, v0
	v_mov_b32_e32 v17, v0
	v_mov_b32_e32 v26, v0
	v_mov_b32_e32 v27, v0
	v_mov_b32_e32 v28, v0
	v_mov_b32_e32 v29, v0
	v_mov_b32_e32 v30, v0
	v_mov_b32_e32 v31, v0
	v_mov_b32_e32 v32, v0
	v_mov_b32_e32 v33, v0
	v_mov_b32_e32 v42, v0
	v_mov_b32_e32 v43, v0
	v_mov_b32_e32 v44, v0
	v_mov_b32_e32 v45, v0
	v_mov_b32_e32 v46, v0
	v_mov_b32_e32 v47, v0
	v_mov_b32_e32 v48, v0
	v_mov_b32_e32 v49, v0
	v_mov_b32_e32 v58, v0
	v_mov_b32_e32 v59, v0
	v_mov_b32_e32 v60, v0
	v_mov_b32_e32 v61, v0
	v_mov_b32_e32 v62, v0
	v_mov_b32_e32 v63, v0
	v_mov_b32_e32 v64, v0
	v_mov_b32_e32 v65, v0
	v_mov_b32_e32 v66, v0
	v_mov_b32_e32 v67, v0
	v_mov_b32_e32 v68, v0
	v_mov_b32_e32 v69, v0
	v_mov_b32_e32 v70, v0
	v_mov_b32_e32 v71, v0
	v_mov_b32_e32 v72, v0
	v_mov_b32_e32 v73, v0
	v_mov_b32_e32 v82, v0
	v_mov_b32_e32 v83, v0
	v_mov_b32_e32 v84, v0
	v_mov_b32_e32 v85, v0
	v_mov_b32_e32 v86, v0
	v_mov_b32_e32 v87, v0
	v_mov_b32_e32 v88, v0
	v_mov_b32_e32 v89, v0
	v_mov_b32_e32 v98, v0
	v_mov_b32_e32 v99, v0
	v_mov_b32_e32 v100, v0
	v_mov_b32_e32 v101, v0
	v_mov_b32_e32 v102, v0
	v_mov_b32_e32 v103, v0
	v_mov_b32_e32 v104, v0
	v_mov_b32_e32 v105, v0
	v_mov_b32_e32 v114, v0
	v_mov_b32_e32 v115, v0
	v_mov_b32_e32 v116, v0
	v_mov_b32_e32 v117, v0
	v_mov_b32_e32 v118, v0
	v_mov_b32_e32 v119, v0
	v_mov_b32_e32 v120, v0
	v_mov_b32_e32 v121, v0
	v_mov_b32_e32 v74, v0
	v_mov_b32_e32 v75, v0
	v_mov_b32_e32 v76, v0
	v_mov_b32_e32 v77, v0
	v_mov_b32_e32 v78, v0
	v_mov_b32_e32 v79, v0
	v_mov_b32_e32 v80, v0
	v_mov_b32_e32 v81, v0
	v_mov_b32_e32 v90, v0
	v_mov_b32_e32 v91, v0
	v_mov_b32_e32 v92, v0
	v_mov_b32_e32 v93, v0
	v_mov_b32_e32 v94, v0
	v_mov_b32_e32 v95, v0
	v_mov_b32_e32 v96, v0
	v_mov_b32_e32 v97, v0
	v_mov_b32_e32 v106, v0
	v_mov_b32_e32 v107, v0
	v_mov_b32_e32 v108, v0
	v_mov_b32_e32 v109, v0
	v_mov_b32_e32 v110, v0
	v_mov_b32_e32 v111, v0
	v_mov_b32_e32 v112, v0
	v_mov_b32_e32 v113, v0
	v_mov_b32_e32 v122, v0
	v_mov_b32_e32 v123, v0
	v_mov_b32_e32 v124, v0
	v_mov_b32_e32 v125, v0
	v_mov_b32_e32 v126, v0
	v_mov_b32_e32 v127, v0
	v_mov_b32_e32 v128, v0
	v_mov_b32_e32 v129, v0
	s_cmp_eq_u32 s36, 1
	s_cbranch_scc1 .LBB0_81
	s_add_u32 s14, s0, 0x100
	s_addc_u32 s15, s1, 0
	s_add_i32 s3, 0, 0x10000
	s_cmpk_eq_i32 s9, 0x7c
	s_cselect_b32 s27, s43, s15
	s_cselect_b32 s26, s42, s14
	v_add_u32_e32 v162, s3, v145
	s_cselect_b32 s23, s79, s8
	s_cselect_b32 s22, s78, s2
	s_add_i32 s4, 0, 0x14000
	ds_read_b128 v[140:143], v162
	ds_read_b128 v[148:151], v162 offset:1024
	ds_read_b128 v[172:175], v162 offset:2048
	ds_read_b128 v[190:193], v162 offset:3072
	v_add_u32_e32 v162, s4, v145
	ds_read_b128 v[194:197], v162
	ds_read_b128 v[198:201], v162 offset:1024
	ds_read_b128 v[202:205], v162 offset:2048
	ds_read_b128 v[206:209], v162 offset:3072
	v_lshl_add_u64 v[162:163], s[0:1], 0, v[136:137]
	s_add_i32 m0, s30, 0xc000
	ds_read_b128 v[210:213], v147
	ds_read_b128 v[214:217], v147 offset:1024
	ds_read_b128 v[218:221], v147 offset:2048
	ds_read_b128 v[222:225], v147 offset:3072
	ds_read_b128 v[226:229], v147 offset:4096
	ds_read_b128 v[230:233], v147 offset:5120
	ds_read_b128 v[234:237], v147 offset:6144
	ds_read_b128 v[238:241], v147 offset:7168
	global_load_lds_dwordx4 v[162:163], off
	v_lshl_add_u64 v[162:163], s[0:1], 0, v[138:139]
	s_add_i32 m0, s30, 0xe000
	s_nop 0
	global_load_lds_dwordx4 v[162:163], off
	s_waitcnt vmcnt(24)
	s_waitcnt lgkmcnt(0)
	s_barrier
	s_setprio 1
	s_waitcnt lgkmcnt(0)
	v_mfma_f32_16x16x32_bf16 v[126:129], v[140:143], v[210:213], v[126:129]
	v_mfma_f32_16x16x32_bf16 v[122:125], v[172:175], v[210:213], v[122:125]
	v_mfma_f32_16x16x32_bf16 v[110:113], v[140:143], v[218:221], v[110:113]
	v_mfma_f32_16x16x32_bf16 v[106:109], v[172:175], v[218:221], v[106:109]
	v_mfma_f32_16x16x32_bf16 v[94:97], v[140:143], v[226:229], v[94:97]
	v_mfma_f32_16x16x32_bf16 v[90:93], v[172:175], v[226:229], v[90:93]
	v_mfma_f32_16x16x32_bf16 v[78:81], v[140:143], v[234:237], v[78:81]
	v_mfma_f32_16x16x32_bf16 v[74:77], v[172:175], v[234:237], v[74:77]
	v_mfma_f32_16x16x32_bf16 v[126:129], v[148:151], v[214:217], v[126:129]
	v_mfma_f32_16x16x32_bf16 v[122:125], v[190:193], v[214:217], v[122:125]
	v_mfma_f32_16x16x32_bf16 v[110:113], v[148:151], v[222:225], v[110:113]
	v_mfma_f32_16x16x32_bf16 v[106:109], v[190:193], v[222:225], v[106:109]
	v_mfma_f32_16x16x32_bf16 v[94:97], v[148:151], v[230:233], v[94:97]
	v_mfma_f32_16x16x32_bf16 v[90:93], v[190:193], v[230:233], v[90:93]
	v_mfma_f32_16x16x32_bf16 v[78:81], v[148:151], v[238:241], v[78:81]
	v_mfma_f32_16x16x32_bf16 v[74:77], v[190:193], v[238:241], v[74:77]
	s_setprio 0
	s_setprio 1
	v_mfma_f32_16x16x32_bf16 v[118:121], v[194:197], v[210:213], v[118:121]
	v_mfma_f32_16x16x32_bf16 v[114:117], v[202:205], v[210:213], v[114:117]
	v_mfma_f32_16x16x32_bf16 v[102:105], v[194:197], v[218:221], v[102:105]
	v_mfma_f32_16x16x32_bf16 v[98:101], v[202:205], v[218:221], v[98:101]
	v_mfma_f32_16x16x32_bf16 v[86:89], v[194:197], v[226:229], v[86:89]
	v_mfma_f32_16x16x32_bf16 v[82:85], v[202:205], v[226:229], v[82:85]
	v_mfma_f32_16x16x32_bf16 v[70:73], v[194:197], v[234:237], v[70:73]
	v_mfma_f32_16x16x32_bf16 v[66:69], v[202:205], v[234:237], v[66:69]
	v_mfma_f32_16x16x32_bf16 v[118:121], v[198:201], v[214:217], v[118:121]
	v_mfma_f32_16x16x32_bf16 v[114:117], v[206:209], v[214:217], v[114:117]
	v_mfma_f32_16x16x32_bf16 v[102:105], v[198:201], v[222:225], v[102:105]
	v_mfma_f32_16x16x32_bf16 v[98:101], v[206:209], v[222:225], v[98:101]
	v_mfma_f32_16x16x32_bf16 v[86:89], v[198:201], v[230:233], v[86:89]
	v_mfma_f32_16x16x32_bf16 v[82:85], v[206:209], v[230:233], v[82:85]
	v_mfma_f32_16x16x32_bf16 v[70:73], v[198:201], v[238:241], v[70:73]
	v_mfma_f32_16x16x32_bf16 v[66:69], v[206:209], v[238:241], v[66:69]
	s_setprio 0
	s_barrier
	s_add_i32 s0, s3, s11
	v_lshl_add_u64 v[162:163], s[22:23], 0, v[4:5]
	s_mov_b32 m0, s0
	ds_read_b128 v[210:213], v147 offset:16384
	ds_read_b128 v[214:217], v147 offset:17408
	ds_read_b128 v[218:221], v147 offset:18432
	ds_read_b128 v[222:225], v147 offset:19456
	ds_read_b128 v[226:229], v147 offset:20480
	ds_read_b128 v[230:233], v147 offset:21504
	ds_read_b128 v[234:237], v147 offset:22528
	ds_read_b128 v[238:241], v147 offset:23552
	global_load_lds_dwordx4 v[162:163], off
	s_add_i32 m0, s0, 0x2000
	s_add_u32 s0, s22, 0x208000
	v_lshl_add_u64 v[166:167], s[22:23], 0, v[130:131]
	s_addc_u32 s1, s23, 0
	s_add_i32 s3, s4, s11
	global_load_lds_dwordx4 v[166:167], off
	v_lshl_add_u64 v[176:177], s[0:1], 0, v[4:5]
	s_mov_b32 m0, s3
	v_lshl_add_u64 v[180:181], s[26:27], 0, v[132:133]
	global_load_lds_dwordx4 v[176:177], off
	v_lshl_add_u64 v[176:177], s[0:1], 0, v[130:131]
	s_add_i32 m0, s3, 0x2000
	s_nop 0
	global_load_lds_dwordx4 v[176:177], off
	v_lshl_add_u64 v[176:177], s[26:27], 0, v[134:135]
	s_mov_b32 m0, s30
	s_nop 0
	global_load_lds_dwordx4 v[176:177], off
	s_mov_b32 m0, s31
	s_nop 0
	global_load_lds_dwordx4 v[180:181], off
	s_waitcnt vmcnt(24)
	s_waitcnt lgkmcnt(0)
	s_barrier
	s_setprio 1
	s_waitcnt lgkmcnt(0)
	v_mfma_f32_16x16x32_bf16 v[62:65], v[140:143], v[210:213], v[62:65]
	v_mfma_f32_16x16x32_bf16 v[58:61], v[172:175], v[210:213], v[58:61]
	v_mfma_f32_16x16x32_bf16 v[46:49], v[140:143], v[218:221], v[46:49]
	v_mfma_f32_16x16x32_bf16 v[42:45], v[172:175], v[218:221], v[42:45]
	v_mfma_f32_16x16x32_bf16 v[30:33], v[140:143], v[226:229], v[30:33]
	v_mfma_f32_16x16x32_bf16 v[26:29], v[172:175], v[226:229], v[26:29]
	v_mfma_f32_16x16x32_bf16 v[14:17], v[140:143], v[234:237], v[14:17]
	v_mfma_f32_16x16x32_bf16 v[10:13], v[172:175], v[234:237], v[10:13]
	v_mfma_f32_16x16x32_bf16 v[62:65], v[148:151], v[214:217], v[62:65]
	v_mfma_f32_16x16x32_bf16 v[58:61], v[190:193], v[214:217], v[58:61]
	v_mfma_f32_16x16x32_bf16 v[46:49], v[148:151], v[222:225], v[46:49]
	v_mfma_f32_16x16x32_bf16 v[42:45], v[190:193], v[222:225], v[42:45]
	v_mfma_f32_16x16x32_bf16 v[30:33], v[148:151], v[230:233], v[30:33]
	v_mfma_f32_16x16x32_bf16 v[26:29], v[190:193], v[230:233], v[26:29]
	v_mfma_f32_16x16x32_bf16 v[14:17], v[148:151], v[238:241], v[14:17]
	v_mfma_f32_16x16x32_bf16 v[10:13], v[190:193], v[238:241], v[10:13]
	s_setprio 0
	s_setprio 1
	v_mfma_f32_16x16x32_bf16 v[54:57], v[194:197], v[210:213], v[54:57]
	v_mfma_f32_16x16x32_bf16 v[50:53], v[202:205], v[210:213], v[50:53]
	v_mfma_f32_16x16x32_bf16 v[38:41], v[194:197], v[218:221], v[38:41]
	v_mfma_f32_16x16x32_bf16 v[34:37], v[202:205], v[218:221], v[34:37]
	v_mfma_f32_16x16x32_bf16 v[22:25], v[194:197], v[226:229], v[22:25]
	v_mfma_f32_16x16x32_bf16 v[18:21], v[202:205], v[226:229], v[18:21]
	v_mfma_f32_16x16x32_bf16 v[6:9], v[194:197], v[234:237], v[6:9]
	v_mfma_f32_16x16x32_bf16 v[0:3], v[202:205], v[234:237], v[0:3]
	v_mfma_f32_16x16x32_bf16 v[54:57], v[198:201], v[214:217], v[54:57]
	v_mfma_f32_16x16x32_bf16 v[50:53], v[206:209], v[214:217], v[50:53]
	v_mfma_f32_16x16x32_bf16 v[38:41], v[198:201], v[222:225], v[38:41]
	v_mfma_f32_16x16x32_bf16 v[34:37], v[206:209], v[222:225], v[34:37]
	v_mfma_f32_16x16x32_bf16 v[22:25], v[198:201], v[230:233], v[22:25]
	v_mfma_f32_16x16x32_bf16 v[18:21], v[206:209], v[230:233], v[18:21]
	v_mfma_f32_16x16x32_bf16 v[6:9], v[198:201], v[238:241], v[6:9]
	v_mfma_f32_16x16x32_bf16 v[0:3], v[206:209], v[238:241], v[0:3]
	s_setprio 0
	s_barrier
	s_branch .Lpeelmid_81

.Lpeelmid_81:
	s_add_i32 s3, 0, 0x18000
	v_add_u32_e32 v164, s3, v145
	s_add_i32 s4, 0, 0x1c000
	ds_read_b128 v[140:143], v164
	ds_read_b128 v[148:151], v164 offset:1024
	ds_read_b128 v[172:175], v164 offset:2048
	ds_read_b128 v[190:193], v164 offset:3072
	v_add_u32_e32 v164, s4, v145
	ds_read_b128 v[194:197], v164
	ds_read_b128 v[198:201], v164 offset:1024
	ds_read_b128 v[202:205], v164 offset:2048
	ds_read_b128 v[206:209], v164 offset:3072
	s_add_u32 s0, s26, 0x208000
	s_addc_u32 s1, s27, 0
	s_mov_b32 m0, s34
	v_lshl_add_u64 v[242:243], s[0:1], 0, v[134:135]
	ds_read_b128 v[210:213], v147 offset:32768
	ds_read_b128 v[214:217], v147 offset:33792
	ds_read_b128 v[218:221], v147 offset:34816
	ds_read_b128 v[222:225], v147 offset:35840
	ds_read_b128 v[226:229], v147 offset:36864
	ds_read_b128 v[230:233], v147 offset:37888
	ds_read_b128 v[234:237], v147 offset:38912
	ds_read_b128 v[238:241], v147 offset:39936
	global_load_lds_dwordx4 v[242:243], off
	v_lshl_add_u64 v[242:243], s[0:1], 0, v[132:133]
	s_mov_b32 m0, s35
	s_nop 0
	global_load_lds_dwordx4 v[242:243], off
	s_waitcnt vmcnt(8)
	s_waitcnt lgkmcnt(0)
	s_barrier
	s_setprio 1
	s_waitcnt lgkmcnt(0)
	v_mfma_f32_16x16x32_bf16 v[126:129], v[140:143], v[210:213], v[126:129]
	v_mfma_f32_16x16x32_bf16 v[122:125], v[172:175], v[210:213], v[122:125]
	v_mfma_f32_16x16x32_bf16 v[110:113], v[140:143], v[218:221], v[110:113]
	v_mfma_f32_16x16x32_bf16 v[106:109], v[172:175], v[218:221], v[106:109]
	v_mfma_f32_16x16x32_bf16 v[94:97], v[140:143], v[226:229], v[94:97]
	v_mfma_f32_16x16x32_bf16 v[90:93], v[172:175], v[226:229], v[90:93]
	v_mfma_f32_16x16x32_bf16 v[78:81], v[140:143], v[234:237], v[78:81]
	v_mfma_f32_16x16x32_bf16 v[74:77], v[172:175], v[234:237], v[74:77]
	v_mfma_f32_16x16x32_bf16 v[126:129], v[148:151], v[214:217], v[126:129]
	v_mfma_f32_16x16x32_bf16 v[122:125], v[190:193], v[214:217], v[122:125]
	v_mfma_f32_16x16x32_bf16 v[110:113], v[148:151], v[222:225], v[110:113]
	v_mfma_f32_16x16x32_bf16 v[106:109], v[190:193], v[222:225], v[106:109]
	v_mfma_f32_16x16x32_bf16 v[94:97], v[148:151], v[230:233], v[94:97]
	v_mfma_f32_16x16x32_bf16 v[90:93], v[190:193], v[230:233], v[90:93]
	v_mfma_f32_16x16x32_bf16 v[78:81], v[148:151], v[238:241], v[78:81]
	v_mfma_f32_16x16x32_bf16 v[74:77], v[190:193], v[238:241], v[74:77]
	s_setprio 0
	s_setprio 1
	v_mfma_f32_16x16x32_bf16 v[118:121], v[194:197], v[210:213], v[118:121]
	v_mfma_f32_16x16x32_bf16 v[114:117], v[202:205], v[210:213], v[114:117]
	v_mfma_f32_16x16x32_bf16 v[102:105], v[194:197], v[218:221], v[102:105]
	v_mfma_f32_16x16x32_bf16 v[98:101], v[202:205], v[218:221], v[98:101]
	v_mfma_f32_16x16x32_bf16 v[86:89], v[194:197], v[226:229], v[86:89]
	v_mfma_f32_16x16x32_bf16 v[82:85], v[202:205], v[226:229], v[82:85]
	v_mfma_f32_16x16x32_bf16 v[70:73], v[194:197], v[234:237], v[70:73]
	v_mfma_f32_16x16x32_bf16 v[66:69], v[202:205], v[234:237], v[66:69]
	v_mfma_f32_16x16x32_bf16 v[118:121], v[198:201], v[214:217], v[118:121]
	v_mfma_f32_16x16x32_bf16 v[114:117], v[206:209], v[214:217], v[114:117]
	v_mfma_f32_16x16x32_bf16 v[102:105], v[198:201], v[222:225], v[102:105]
	v_mfma_f32_16x16x32_bf16 v[98:101], v[206:209], v[222:225], v[98:101]
	v_mfma_f32_16x16x32_bf16 v[86:89], v[198:201], v[230:233], v[86:89]
	v_mfma_f32_16x16x32_bf16 v[82:85], v[206:209], v[230:233], v[82:85]
	v_mfma_f32_16x16x32_bf16 v[70:73], v[198:201], v[238:241], v[70:73]
	v_mfma_f32_16x16x32_bf16 v[66:69], v[206:209], v[238:241], v[66:69]
	s_setprio 0
	s_barrier
	s_add_i32 s0, s3, s11
	v_lshl_add_u64 v[162:163], v[162:163], 0, s[70:71]
	s_mov_b32 m0, s0
	ds_read_b128 v[210:213], v147 offset:49152
	ds_read_b128 v[214:217], v147 offset:50176
	ds_read_b128 v[218:221], v147 offset:51200
	ds_read_b128 v[222:225], v147 offset:52224
	ds_read_b128 v[226:229], v147 offset:53248
	ds_read_b128 v[230:233], v147 offset:54272
	ds_read_b128 v[234:237], v147 offset:55296
	ds_read_b128 v[238:241], v147 offset:56320
	global_load_lds_dwordx4 v[162:163], off
	s_add_i32 m0, s0, 0x2000
	s_add_u32 s0, s22, 0x208080
	v_lshl_add_u64 v[162:163], v[166:167], 0, s[70:71]
	s_addc_u32 s1, s23, 0
	s_add_i32 s3, s4, s11
	global_load_lds_dwordx4 v[162:163], off
	v_lshl_add_u64 v[162:163], s[0:1], 0, v[4:5]
	s_mov_b32 m0, s3
	s_nop 0
	global_load_lds_dwordx4 v[162:163], off
	v_lshl_add_u64 v[162:163], s[0:1], 0, v[130:131]
	s_add_i32 m0, s3, 0x2000
	s_nop 0
	global_load_lds_dwordx4 v[162:163], off
	v_lshl_add_u64 v[162:163], v[176:177], 0, s[70:71]
	s_mov_b32 m0, s51
	s_nop 0
	global_load_lds_dwordx4 v[162:163], off
	v_lshl_add_u64 v[162:163], v[180:181], 0, s[70:71]
	s_mov_b32 m0, s52
	s_nop 0
	global_load_lds_dwordx4 v[162:163], off
	s_waitcnt vmcnt(8)
	s_waitcnt lgkmcnt(0)
	s_barrier
	s_setprio 1
	s_waitcnt lgkmcnt(0)
	v_mfma_f32_16x16x32_bf16 v[62:65], v[140:143], v[210:213], v[62:65]
	v_mfma_f32_16x16x32_bf16 v[58:61], v[172:175], v[210:213], v[58:61]
	v_mfma_f32_16x16x32_bf16 v[46:49], v[140:143], v[218:221], v[46:49]
	v_mfma_f32_16x16x32_bf16 v[42:45], v[172:175], v[218:221], v[42:45]
	v_mfma_f32_16x16x32_bf16 v[30:33], v[140:143], v[226:229], v[30:33]
	v_mfma_f32_16x16x32_bf16 v[26:29], v[172:175], v[226:229], v[26:29]
	v_mfma_f32_16x16x32_bf16 v[14:17], v[140:143], v[234:237], v[14:17]
	v_mfma_f32_16x16x32_bf16 v[10:13], v[172:175], v[234:237], v[10:13]
	v_mfma_f32_16x16x32_bf16 v[62:65], v[148:151], v[214:217], v[62:65]
	v_mfma_f32_16x16x32_bf16 v[58:61], v[190:193], v[214:217], v[58:61]
	v_mfma_f32_16x16x32_bf16 v[46:49], v[148:151], v[222:225], v[46:49]
	v_mfma_f32_16x16x32_bf16 v[42:45], v[190:193], v[222:225], v[42:45]
	v_mfma_f32_16x16x32_bf16 v[30:33], v[148:151], v[230:233], v[30:33]
	v_mfma_f32_16x16x32_bf16 v[26:29], v[190:193], v[230:233], v[26:29]
	v_mfma_f32_16x16x32_bf16 v[14:17], v[148:151], v[238:241], v[14:17]
	v_mfma_f32_16x16x32_bf16 v[10:13], v[190:193], v[238:241], v[10:13]
	s_setprio 0
	s_setprio 1
	v_mfma_f32_16x16x32_bf16 v[54:57], v[194:197], v[210:213], v[54:57]
	v_mfma_f32_16x16x32_bf16 v[50:53], v[202:205], v[210:213], v[50:53]
	v_mfma_f32_16x16x32_bf16 v[38:41], v[194:197], v[218:221], v[38:41]
	v_mfma_f32_16x16x32_bf16 v[34:37], v[202:205], v[218:221], v[34:37]
	v_mfma_f32_16x16x32_bf16 v[22:25], v[194:197], v[226:229], v[22:25]
	v_mfma_f32_16x16x32_bf16 v[18:21], v[202:205], v[226:229], v[18:21]
	v_mfma_f32_16x16x32_bf16 v[6:9], v[194:197], v[234:237], v[6:9]
	v_mfma_f32_16x16x32_bf16 v[0:3], v[202:205], v[234:237], v[0:3]
	v_mfma_f32_16x16x32_bf16 v[54:57], v[198:201], v[214:217], v[54:57]
	v_mfma_f32_16x16x32_bf16 v[50:53], v[206:209], v[214:217], v[50:53]
	v_mfma_f32_16x16x32_bf16 v[38:41], v[198:201], v[222:225], v[38:41]
	v_mfma_f32_16x16x32_bf16 v[34:37], v[206:209], v[222:225], v[34:37]
	v_mfma_f32_16x16x32_bf16 v[22:25], v[198:201], v[230:233], v[22:25]
	v_mfma_f32_16x16x32_bf16 v[18:21], v[206:209], v[230:233], v[18:21]
	v_mfma_f32_16x16x32_bf16 v[6:9], v[198:201], v[238:241], v[6:9]
	v_mfma_f32_16x16x32_bf16 v[0:3], v[206:209], v[238:241], v[0:3]
	s_setprio 0
	s_barrier
	s_add_i32 s9, s9, 2
	s_add_u32 s2, s2, 0x100
	s_addc_u32 s8, s8, 0
	s_cmpk_gt_u32 s9, 0x7d
	s_mov_b64 s[0:1], s[14:15]
	s_cbranch_scc0 .LBB0_81
	s_and_b64 vcc, exec, s[48:49]
	s_cbranch_vccz .LBB0_84
	s_barrier

.LBB0_123:
	s_ashr_i32 s3, s51, 24
	s_lshl_b32 s2, s51, 8
	s_andn2_b32 s3, s3, 63
	s_add_i32 s2, s3, s2
	s_ashr_i32 s3, s2, 31
	s_lshl_b64 s[2:3], s[2:3], 12
	s_add_u32 s48, s11, s2
	s_addc_u32 s49, s26, s3
	s_and_b64 s[2:3], s[38:39], exec
	s_cselect_b32 s2, s49, s1
	s_cselect_b32 s8, s48, s0
	s_ashr_i32 s47, s46, 31
	s_lshl_b64 s[4:5], s[46:47], 20
	v_readlane_b32 s6, v254, 1
	v_readlane_b32 s7, v254, 2
	s_add_u32 s78, s6, s4
	s_addc_u32 s79, s7, s5
	s_and_b64 s[4:5], s[38:39], exec
	s_cselect_b32 s10, s79, s15
	s_cselect_b32 s24, s78, s14
	s_add_u32 s22, s0, 0x80080
	s_addc_u32 s23, s1, 0
	s_add_u32 s9, s14, 0x100
	v_mov_b32_e32 v0, 0
	s_addc_u32 s25, s15, 0
	s_mov_b32 s28, -2
	v_mov_b32_e32 v1, v0
	v_mov_b32_e32 v2, v0
	v_mov_b32_e32 v3, v0
	v_mov_b32_e32 v6, v0
	v_mov_b32_e32 v7, v0
	v_mov_b32_e32 v8, v0
	v_mov_b32_e32 v9, v0
	v_mov_b32_e32 v10, v0
	v_mov_b32_e32 v11, v0
	v_mov_b32_e32 v12, v0
	v_mov_b32_e32 v13, v0
	v_mov_b32_e32 v14, v0
	v_mov_b32_e32 v15, v0
	v_mov_b32_e32 v16, v0
	v_mov_b32_e32 v17, v0
	v_mov_b32_e32 v18, v0
	v_mov_b32_e32 v19, v0
	v_mov_b32_e32 v20, v0
	v_mov_b32_e32 v21, v0
	v_mov_b32_e32 v22, v0
	v_mov_b32_e32 v23, v0
	v_mov_b32_e32 v24, v0
	v_mov_b32_e32 v25, v0
	v_mov_b32_e32 v26, v0
	v_mov_b32_e32 v27, v0
	v_mov_b32_e32 v28, v0
	v_mov_b32_e32 v29, v0
	v_mov_b32_e32 v30, v0
	v_mov_b32_e32 v31, v0
	v_mov_b32_e32 v32, v0
	v_mov_b32_e32 v33, v0
	v_mov_b32_e32 v58, v0
	v_mov_b32_e32 v59, v0
	v_mov_b32_e32 v60, v0
	v_mov_b32_e32 v61, v0
	v_mov_b32_e32 v62, v0
	v_mov_b32_e32 v63, v0
	v_mov_b32_e32 v64, v0
	v_mov_b32_e32 v65, v0
	v_mov_b32_e32 v74, v0
	v_mov_b32_e32 v75, v0
	v_mov_b32_e32 v76, v0
	v_mov_b32_e32 v77, v0
	v_mov_b32_e32 v78, v0
	v_mov_b32_e32 v79, v0
	v_mov_b32_e32 v80, v0
	v_mov_b32_e32 v81, v0
	v_mov_b32_e32 v82, v0
	v_mov_b32_e32 v83, v0
	v_mov_b32_e32 v84, v0
	v_mov_b32_e32 v85, v0
	v_mov_b32_e32 v86, v0
	v_mov_b32_e32 v87, v0
	v_mov_b32_e32 v88, v0
	v_mov_b32_e32 v89, v0
	v_mov_b32_e32 v90, v0
	v_mov_b32_e32 v91, v0
	v_mov_b32_e32 v92, v0
	v_mov_b32_e32 v93, v0
	v_mov_b32_e32 v94, v0
	v_mov_b32_e32 v95, v0
	v_mov_b32_e32 v96, v0
	v_mov_b32_e32 v97, v0
	v_mov_b32_e32 v34, v0
	v_mov_b32_e32 v35, v0
	v_mov_b32_e32 v36, v0
	v_mov_b32_e32 v37, v0
	v_mov_b32_e32 v38, v0
	v_mov_b32_e32 v39, v0
	v_mov_b32_e32 v40, v0
	v_mov_b32_e32 v41, v0
	v_mov_b32_e32 v42, v0
	v_mov_b32_e32 v43, v0
	v_mov_b32_e32 v44, v0
	v_mov_b32_e32 v45, v0
	v_mov_b32_e32 v46, v0
	v_mov_b32_e32 v47, v0
	v_mov_b32_e32 v48, v0
	v_mov_b32_e32 v49, v0
	v_mov_b32_e32 v50, v0
	v_mov_b32_e32 v51, v0
	v_mov_b32_e32 v52, v0
	v_mov_b32_e32 v53, v0
	v_mov_b32_e32 v54, v0
	v_mov_b32_e32 v55, v0
	v_mov_b32_e32 v56, v0
	v_mov_b32_e32 v57, v0
	v_mov_b32_e32 v66, v0
	v_mov_b32_e32 v67, v0
	v_mov_b32_e32 v68, v0
	v_mov_b32_e32 v69, v0
	v_mov_b32_e32 v70, v0
	v_mov_b32_e32 v71, v0
	v_mov_b32_e32 v72, v0
	v_mov_b32_e32 v73, v0
	v_mov_b32_e32 v98, v0
	v_mov_b32_e32 v99, v0
	v_mov_b32_e32 v100, v0
	v_mov_b32_e32 v101, v0
	v_mov_b32_e32 v102, v0
	v_mov_b32_e32 v103, v0
	v_mov_b32_e32 v104, v0
	v_mov_b32_e32 v105, v0
	v_mov_b32_e32 v106, v0
	v_mov_b32_e32 v107, v0
	v_mov_b32_e32 v108, v0
	v_mov_b32_e32 v109, v0
	v_mov_b32_e32 v110, v0
	v_mov_b32_e32 v111, v0
	v_mov_b32_e32 v112, v0
	v_mov_b32_e32 v113, v0
	v_mov_b32_e32 v114, v0
	v_mov_b32_e32 v115, v0
	v_mov_b32_e32 v116, v0
	v_mov_b32_e32 v117, v0
	v_mov_b32_e32 v118, v0
	v_mov_b32_e32 v119, v0
	v_mov_b32_e32 v120, v0
	v_mov_b32_e32 v121, v0
	v_mov_b32_e32 v122, v0
	v_mov_b32_e32 v123, v0
	v_mov_b32_e32 v124, v0
	v_mov_b32_e32 v125, v0
	v_mov_b32_e32 v126, v0
	v_mov_b32_e32 v127, v0
	v_mov_b32_e32 v128, v0
	v_mov_b32_e32 v129, v0
	s_cmp_eq_u32 s50, 1
	s_cbranch_scc1 .LBB0_124
	s_add_u32 s0, s22, 0xfff80080
	s_addc_u32 s1, s23, -1
	s_add_i32 s3, 0, 0x10000
	s_cmp_eq_u32 s28, 28
	s_cselect_b32 s15, s2, s1
	s_cselect_b32 s14, s8, s0
	v_add_u32_e32 v162, s3, v141
	s_cselect_b32 s1, s10, s25
	s_cselect_b32 s0, s24, s9
	s_add_i32 s6, 0, 0x14000
	ds_read_b128 v[144:147], v162
	ds_read_b128 v[148:151], v162 offset:1024
	ds_read_b128 v[172:175], v162 offset:2048
	ds_read_b128 v[190:193], v162 offset:3072
	v_add_u32_e32 v162, s6, v141
	ds_read_b128 v[194:197], v162
	ds_read_b128 v[198:201], v162 offset:1024
	ds_read_b128 v[202:205], v162 offset:2048
	ds_read_b128 v[206:209], v162 offset:3072
	v_lshl_add_u64 v[162:163], s[22:23], 0, v[136:137]
	s_add_i32 m0, s30, 0xc000
	ds_read_b128 v[210:213], v143
	ds_read_b128 v[214:217], v143 offset:1024
	ds_read_b128 v[218:221], v143 offset:2048
	ds_read_b128 v[222:225], v143 offset:3072
	ds_read_b128 v[226:229], v143 offset:4096
	ds_read_b128 v[230:233], v143 offset:5120
	ds_read_b128 v[234:237], v143 offset:6144
	ds_read_b128 v[238:241], v143 offset:7168
	global_load_lds_dwordx4 v[162:163], off
	v_lshl_add_u64 v[162:163], s[22:23], 0, v[138:139]
	s_add_i32 m0, s30, 0xe000
	s_nop 0
	global_load_lds_dwordx4 v[162:163], off
	s_waitcnt vmcnt(24)
	s_waitcnt lgkmcnt(0)
	s_barrier
	s_setprio 1
	s_waitcnt lgkmcnt(0)
	v_mfma_f32_16x16x32_bf16 v[126:129], v[144:147], v[210:213], v[126:129]
	v_mfma_f32_16x16x32_bf16 v[122:125], v[172:175], v[210:213], v[122:125]
	v_mfma_f32_16x16x32_bf16 v[118:121], v[144:147], v[218:221], v[118:121]
	v_mfma_f32_16x16x32_bf16 v[114:117], v[172:175], v[218:221], v[114:117]
	v_mfma_f32_16x16x32_bf16 v[110:113], v[144:147], v[226:229], v[110:113]
	v_mfma_f32_16x16x32_bf16 v[106:109], v[172:175], v[226:229], v[106:109]
	v_mfma_f32_16x16x32_bf16 v[102:105], v[144:147], v[234:237], v[102:105]
	v_mfma_f32_16x16x32_bf16 v[98:101], v[172:175], v[234:237], v[98:101]
	v_mfma_f32_16x16x32_bf16 v[126:129], v[148:151], v[214:217], v[126:129]
	v_mfma_f32_16x16x32_bf16 v[122:125], v[190:193], v[214:217], v[122:125]
	v_mfma_f32_16x16x32_bf16 v[118:121], v[148:151], v[222:225], v[118:121]
	v_mfma_f32_16x16x32_bf16 v[114:117], v[190:193], v[222:225], v[114:117]
	v_mfma_f32_16x16x32_bf16 v[110:113], v[148:151], v[230:233], v[110:113]
	v_mfma_f32_16x16x32_bf16 v[106:109], v[190:193], v[230:233], v[106:109]
	v_mfma_f32_16x16x32_bf16 v[102:105], v[148:151], v[238:241], v[102:105]
	v_mfma_f32_16x16x32_bf16 v[98:101], v[190:193], v[238:241], v[98:101]
	s_setprio 0
	s_setprio 1
	v_mfma_f32_16x16x32_bf16 v[70:73], v[194:197], v[210:213], v[70:73]
	v_mfma_f32_16x16x32_bf16 v[66:69], v[202:205], v[210:213], v[66:69]
	v_mfma_f32_16x16x32_bf16 v[54:57], v[194:197], v[218:221], v[54:57]
	v_mfma_f32_16x16x32_bf16 v[50:53], v[202:205], v[218:221], v[50:53]
	v_mfma_f32_16x16x32_bf16 v[46:49], v[194:197], v[226:229], v[46:49]
	v_mfma_f32_16x16x32_bf16 v[42:45], v[202:205], v[226:229], v[42:45]
	v_mfma_f32_16x16x32_bf16 v[38:41], v[194:197], v[234:237], v[38:41]
	v_mfma_f32_16x16x32_bf16 v[34:37], v[202:205], v[234:237], v[34:37]
	v_mfma_f32_16x16x32_bf16 v[70:73], v[198:201], v[214:217], v[70:73]
	v_mfma_f32_16x16x32_bf16 v[66:69], v[206:209], v[214:217], v[66:69]
	v_mfma_f32_16x16x32_bf16 v[54:57], v[198:201], v[222:225], v[54:57]
	v_mfma_f32_16x16x32_bf16 v[50:53], v[206:209], v[222:225], v[50:53]
	v_mfma_f32_16x16x32_bf16 v[46:49], v[198:201], v[230:233], v[46:49]
	v_mfma_f32_16x16x32_bf16 v[42:45], v[206:209], v[230:233], v[42:45]
	v_mfma_f32_16x16x32_bf16 v[38:41], v[198:201], v[238:241], v[38:41]
	v_mfma_f32_16x16x32_bf16 v[34:37], v[206:209], v[238:241], v[34:37]
	s_setprio 0
	s_barrier
	s_add_i32 s3, s3, s27
	v_lshl_add_u64 v[162:163], s[0:1], 0, v[4:5]
	s_mov_b32 m0, s3
	ds_read_b128 v[210:213], v143 offset:16384
	ds_read_b128 v[214:217], v143 offset:17408
	ds_read_b128 v[218:221], v143 offset:18432
	ds_read_b128 v[222:225], v143 offset:19456
	ds_read_b128 v[226:229], v143 offset:20480
	ds_read_b128 v[230:233], v143 offset:21504
	ds_read_b128 v[234:237], v143 offset:22528
	ds_read_b128 v[238:241], v143 offset:23552
	global_load_lds_dwordx4 v[162:163], off
	s_add_i32 m0, s3, 0x2000
	s_add_u32 s4, s0, 0x80000
	v_lshl_add_u64 v[166:167], s[0:1], 0, v[130:131]
	s_addc_u32 s5, s1, 0
	s_add_i32 s3, s6, s27
	global_load_lds_dwordx4 v[166:167], off
	v_lshl_add_u64 v[176:177], s[4:5], 0, v[4:5]
	s_mov_b32 m0, s3
	v_lshl_add_u64 v[180:181], s[14:15], 0, v[132:133]
	global_load_lds_dwordx4 v[176:177], off
	v_lshl_add_u64 v[176:177], s[4:5], 0, v[130:131]
	s_add_i32 m0, s3, 0x2000
	s_nop 0
	global_load_lds_dwordx4 v[176:177], off
	v_lshl_add_u64 v[176:177], s[14:15], 0, v[134:135]
	s_mov_b32 m0, s30
	s_nop 0
	global_load_lds_dwordx4 v[176:177], off
	s_mov_b32 m0, s31
	s_nop 0
	global_load_lds_dwordx4 v[180:181], off
	s_waitcnt vmcnt(24)
	s_waitcnt lgkmcnt(0)
	s_barrier
	s_setprio 1
	s_waitcnt lgkmcnt(0)
	v_mfma_f32_16x16x32_bf16 v[94:97], v[144:147], v[210:213], v[94:97]
	v_mfma_f32_16x16x32_bf16 v[90:93], v[172:175], v[210:213], v[90:93]
	v_mfma_f32_16x16x32_bf16 v[86:89], v[144:147], v[218:221], v[86:89]
	v_mfma_f32_16x16x32_bf16 v[82:85], v[172:175], v[218:221], v[82:85]
	v_mfma_f32_16x16x32_bf16 v[78:81], v[144:147], v[226:229], v[78:81]
	v_mfma_f32_16x16x32_bf16 v[74:77], v[172:175], v[226:229], v[74:77]
	v_mfma_f32_16x16x32_bf16 v[62:65], v[144:147], v[234:237], v[62:65]
	v_mfma_f32_16x16x32_bf16 v[58:61], v[172:175], v[234:237], v[58:61]
	v_mfma_f32_16x16x32_bf16 v[94:97], v[148:151], v[214:217], v[94:97]
	v_mfma_f32_16x16x32_bf16 v[90:93], v[190:193], v[214:217], v[90:93]
	v_mfma_f32_16x16x32_bf16 v[86:89], v[148:151], v[222:225], v[86:89]
	v_mfma_f32_16x16x32_bf16 v[82:85], v[190:193], v[222:225], v[82:85]
	v_mfma_f32_16x16x32_bf16 v[78:81], v[148:151], v[230:233], v[78:81]
	v_mfma_f32_16x16x32_bf16 v[74:77], v[190:193], v[230:233], v[74:77]
	v_mfma_f32_16x16x32_bf16 v[62:65], v[148:151], v[238:241], v[62:65]
	v_mfma_f32_16x16x32_bf16 v[58:61], v[190:193], v[238:241], v[58:61]
	s_setprio 0
	s_setprio 1
	v_mfma_f32_16x16x32_bf16 v[30:33], v[194:197], v[210:213], v[30:33]
	v_mfma_f32_16x16x32_bf16 v[26:29], v[202:205], v[210:213], v[26:29]
	v_mfma_f32_16x16x32_bf16 v[22:25], v[194:197], v[218:221], v[22:25]
	v_mfma_f32_16x16x32_bf16 v[18:21], v[202:205], v[218:221], v[18:21]
	v_mfma_f32_16x16x32_bf16 v[14:17], v[194:197], v[226:229], v[14:17]
	v_mfma_f32_16x16x32_bf16 v[10:13], v[202:205], v[226:229], v[10:13]
	v_mfma_f32_16x16x32_bf16 v[6:9], v[194:197], v[234:237], v[6:9]
	v_mfma_f32_16x16x32_bf16 v[0:3], v[202:205], v[234:237], v[0:3]
	v_mfma_f32_16x16x32_bf16 v[30:33], v[198:201], v[214:217], v[30:33]
	v_mfma_f32_16x16x32_bf16 v[26:29], v[206:209], v[214:217], v[26:29]
	v_mfma_f32_16x16x32_bf16 v[22:25], v[198:201], v[222:225], v[22:25]
	v_mfma_f32_16x16x32_bf16 v[18:21], v[206:209], v[222:225], v[18:21]
	v_mfma_f32_16x16x32_bf16 v[14:17], v[198:201], v[230:233], v[14:17]
	v_mfma_f32_16x16x32_bf16 v[10:13], v[206:209], v[230:233], v[10:13]
	v_mfma_f32_16x16x32_bf16 v[6:9], v[198:201], v[238:241], v[6:9]
	v_mfma_f32_16x16x32_bf16 v[0:3], v[206:209], v[238:241], v[0:3]
	s_setprio 0
	s_barrier
	s_branch .Lpeelmid_124

.Lpeelmid_124:
	s_add_i32 s3, 0, 0x18000
	v_add_u32_e32 v164, s3, v141
	s_add_i32 s6, 0, 0x1c000
	ds_read_b128 v[144:147], v164
	ds_read_b128 v[148:151], v164 offset:1024
	ds_read_b128 v[172:175], v164 offset:2048
	ds_read_b128 v[190:193], v164 offset:3072
	v_add_u32_e32 v164, s6, v141
	ds_read_b128 v[194:197], v164
	ds_read_b128 v[198:201], v164 offset:1024
	ds_read_b128 v[202:205], v164 offset:2048
	ds_read_b128 v[206:209], v164 offset:3072
	s_add_u32 s4, s14, 0x80000
	s_addc_u32 s5, s15, 0
	s_mov_b32 m0, s34
	v_lshl_add_u64 v[242:243], s[4:5], 0, v[134:135]
	ds_read_b128 v[210:213], v143 offset:32768
	ds_read_b128 v[214:217], v143 offset:33792
	ds_read_b128 v[218:221], v143 offset:34816
	ds_read_b128 v[222:225], v143 offset:35840
	ds_read_b128 v[226:229], v143 offset:36864
	ds_read_b128 v[230:233], v143 offset:37888
	ds_read_b128 v[234:237], v143 offset:38912
	ds_read_b128 v[238:241], v143 offset:39936
	global_load_lds_dwordx4 v[242:243], off
	v_lshl_add_u64 v[242:243], s[4:5], 0, v[132:133]
	s_mov_b32 m0, s35
	s_nop 0
	global_load_lds_dwordx4 v[242:243], off
	s_waitcnt vmcnt(8)
	s_waitcnt lgkmcnt(0)
	s_barrier
	s_setprio 1
	s_waitcnt lgkmcnt(0)
	v_mfma_f32_16x16x32_bf16 v[126:129], v[144:147], v[210:213], v[126:129]
	v_mfma_f32_16x16x32_bf16 v[122:125], v[172:175], v[210:213], v[122:125]
	v_mfma_f32_16x16x32_bf16 v[118:121], v[144:147], v[218:221], v[118:121]
	v_mfma_f32_16x16x32_bf16 v[114:117], v[172:175], v[218:221], v[114:117]
	v_mfma_f32_16x16x32_bf16 v[110:113], v[144:147], v[226:229], v[110:113]
	v_mfma_f32_16x16x32_bf16 v[106:109], v[172:175], v[226:229], v[106:109]
	v_mfma_f32_16x16x32_bf16 v[102:105], v[144:147], v[234:237], v[102:105]
	v_mfma_f32_16x16x32_bf16 v[98:101], v[172:175], v[234:237], v[98:101]
	v_mfma_f32_16x16x32_bf16 v[126:129], v[148:151], v[214:217], v[126:129]
	v_mfma_f32_16x16x32_bf16 v[122:125], v[190:193], v[214:217], v[122:125]
	v_mfma_f32_16x16x32_bf16 v[118:121], v[148:151], v[222:225], v[118:121]
	v_mfma_f32_16x16x32_bf16 v[114:117], v[190:193], v[222:225], v[114:117]
	v_mfma_f32_16x16x32_bf16 v[110:113], v[148:151], v[230:233], v[110:113]
	v_mfma_f32_16x16x32_bf16 v[106:109], v[190:193], v[230:233], v[106:109]
	v_mfma_f32_16x16x32_bf16 v[102:105], v[148:151], v[238:241], v[102:105]
	v_mfma_f32_16x16x32_bf16 v[98:101], v[190:193], v[238:241], v[98:101]
	s_setprio 0
	s_setprio 1
	v_mfma_f32_16x16x32_bf16 v[70:73], v[194:197], v[210:213], v[70:73]
	v_mfma_f32_16x16x32_bf16 v[66:69], v[202:205], v[210:213], v[66:69]
	v_mfma_f32_16x16x32_bf16 v[54:57], v[194:197], v[218:221], v[54:57]
	v_mfma_f32_16x16x32_bf16 v[50:53], v[202:205], v[218:221], v[50:53]
	v_mfma_f32_16x16x32_bf16 v[46:49], v[194:197], v[226:229], v[46:49]
	v_mfma_f32_16x16x32_bf16 v[42:45], v[202:205], v[226:229], v[42:45]
	v_mfma_f32_16x16x32_bf16 v[38:41], v[194:197], v[234:237], v[38:41]
	v_mfma_f32_16x16x32_bf16 v[34:37], v[202:205], v[234:237], v[34:37]
	v_mfma_f32_16x16x32_bf16 v[70:73], v[198:201], v[214:217], v[70:73]
	v_mfma_f32_16x16x32_bf16 v[66:69], v[206:209], v[214:217], v[66:69]
	v_mfma_f32_16x16x32_bf16 v[54:57], v[198:201], v[222:225], v[54:57]
	v_mfma_f32_16x16x32_bf16 v[50:53], v[206:209], v[222:225], v[50:53]
	v_mfma_f32_16x16x32_bf16 v[46:49], v[198:201], v[230:233], v[46:49]
	v_mfma_f32_16x16x32_bf16 v[42:45], v[206:209], v[230:233], v[42:45]
	v_mfma_f32_16x16x32_bf16 v[38:41], v[198:201], v[238:241], v[38:41]
	v_mfma_f32_16x16x32_bf16 v[34:37], v[206:209], v[238:241], v[34:37]
	s_setprio 0
	s_barrier
	s_add_i32 s3, s3, s27
	v_lshl_add_u64 v[162:163], v[162:163], 0, s[70:71]
	s_mov_b32 m0, s3
	ds_read_b128 v[210:213], v143 offset:49152
	ds_read_b128 v[214:217], v143 offset:50176
	ds_read_b128 v[218:221], v143 offset:51200
	ds_read_b128 v[222:225], v143 offset:52224
	ds_read_b128 v[226:229], v143 offset:53248
	ds_read_b128 v[230:233], v143 offset:54272
	ds_read_b128 v[234:237], v143 offset:55296
	ds_read_b128 v[238:241], v143 offset:56320
	global_load_lds_dwordx4 v[162:163], off
	s_add_i32 m0, s3, 0x2000
	s_add_u32 s0, s0, 0x80080
	v_lshl_add_u64 v[162:163], v[166:167], 0, s[70:71]
	s_addc_u32 s1, s1, 0
	s_add_i32 s3, s6, s27
	global_load_lds_dwordx4 v[162:163], off
	v_lshl_add_u64 v[162:163], s[0:1], 0, v[4:5]
	s_mov_b32 m0, s3
	s_nop 0
	global_load_lds_dwordx4 v[162:163], off
	v_lshl_add_u64 v[162:163], s[0:1], 0, v[130:131]
	s_add_i32 m0, s3, 0x2000
	s_nop 0
	global_load_lds_dwordx4 v[162:163], off
	v_lshl_add_u64 v[162:163], v[176:177], 0, s[70:71]
	s_mov_b32 m0, s36
	s_nop 0
	global_load_lds_dwordx4 v[162:163], off
	v_lshl_add_u64 v[162:163], v[180:181], 0, s[70:71]
	s_mov_b32 m0, s37
	s_nop 0
	global_load_lds_dwordx4 v[162:163], off
	s_waitcnt vmcnt(8)
	s_waitcnt lgkmcnt(0)
	s_barrier
	s_setprio 1
	s_waitcnt lgkmcnt(0)
	v_mfma_f32_16x16x32_bf16 v[94:97], v[144:147], v[210:213], v[94:97]
	v_mfma_f32_16x16x32_bf16 v[90:93], v[172:175], v[210:213], v[90:93]
	v_mfma_f32_16x16x32_bf16 v[86:89], v[144:147], v[218:221], v[86:89]
	v_mfma_f32_16x16x32_bf16 v[82:85], v[172:175], v[218:221], v[82:85]
	v_mfma_f32_16x16x32_bf16 v[78:81], v[144:147], v[226:229], v[78:81]
	v_mfma_f32_16x16x32_bf16 v[74:77], v[172:175], v[226:229], v[74:77]
	v_mfma_f32_16x16x32_bf16 v[62:65], v[144:147], v[234:237], v[62:65]
	v_mfma_f32_16x16x32_bf16 v[58:61], v[172:175], v[234:237], v[58:61]
	v_mfma_f32_16x16x32_bf16 v[94:97], v[148:151], v[214:217], v[94:97]
	v_mfma_f32_16x16x32_bf16 v[90:93], v[190:193], v[214:217], v[90:93]
	v_mfma_f32_16x16x32_bf16 v[86:89], v[148:151], v[222:225], v[86:89]
	v_mfma_f32_16x16x32_bf16 v[82:85], v[190:193], v[222:225], v[82:85]
	v_mfma_f32_16x16x32_bf16 v[78:81], v[148:151], v[230:233], v[78:81]
	v_mfma_f32_16x16x32_bf16 v[74:77], v[190:193], v[230:233], v[74:77]
	v_mfma_f32_16x16x32_bf16 v[62:65], v[148:151], v[238:241], v[62:65]
	v_mfma_f32_16x16x32_bf16 v[58:61], v[190:193], v[238:241], v[58:61]
	s_setprio 0
	s_setprio 1
	v_mfma_f32_16x16x32_bf16 v[30:33], v[194:197], v[210:213], v[30:33]
	v_mfma_f32_16x16x32_bf16 v[26:29], v[202:205], v[210:213], v[26:29]
	v_mfma_f32_16x16x32_bf16 v[22:25], v[194:197], v[218:221], v[22:25]
	v_mfma_f32_16x16x32_bf16 v[18:21], v[202:205], v[218:221], v[18:21]
	v_mfma_f32_16x16x32_bf16 v[14:17], v[194:197], v[226:229], v[14:17]
	v_mfma_f32_16x16x32_bf16 v[10:13], v[202:205], v[226:229], v[10:13]
	v_mfma_f32_16x16x32_bf16 v[6:9], v[194:197], v[234:237], v[6:9]
	v_mfma_f32_16x16x32_bf16 v[0:3], v[202:205], v[234:237], v[0:3]
	v_mfma_f32_16x16x32_bf16 v[30:33], v[198:201], v[214:217], v[30:33]
	v_mfma_f32_16x16x32_bf16 v[26:29], v[206:209], v[214:217], v[26:29]
	v_mfma_f32_16x16x32_bf16 v[22:25], v[198:201], v[222:225], v[22:25]
	v_mfma_f32_16x16x32_bf16 v[18:21], v[206:209], v[222:225], v[18:21]
	v_mfma_f32_16x16x32_bf16 v[14:17], v[198:201], v[230:233], v[14:17]
	v_mfma_f32_16x16x32_bf16 v[10:13], v[206:209], v[230:233], v[10:13]
	v_mfma_f32_16x16x32_bf16 v[6:9], v[198:201], v[238:241], v[6:9]
	v_mfma_f32_16x16x32_bf16 v[0:3], v[206:209], v[238:241], v[0:3]
	s_setprio 0
	s_barrier
	s_add_i32 s28, s28, 2
	s_add_u32 s22, s22, 0x100
	s_addc_u32 s23, s23, 0
	s_add_u32 s9, s9, 0x100
	s_addc_u32 s25, s25, 0
	s_cmp_gt_u32 s28, 29
	s_cbranch_scc0 .LBB0_124
	s_and_b64 vcc, exec, s[42:43]
	s_cbranch_vccz .LBB0_127
	s_barrier

.LBB0_162:
	s_ashr_i32 s49, s48, 31
	s_lshl_b64 s[2:3], s[48:49], 20
	v_readlane_b32 s4, v253, 61
	v_readlane_b32 s5, v253, 62
	s_add_u32 s82, s4, s2
	s_addc_u32 s83, s5, s3
	s_and_b64 s[2:3], s[42:43], exec
	s_cselect_b32 s2, s83, s1
	s_cselect_b32 s8, s82, s0
	s_add_u32 s22, s14, 0x80080
	s_addc_u32 s23, s15, 0
	s_add_u32 s9, s0, 0x100
	v_mov_b32_e32 v0, 0
	s_addc_u32 s10, s1, 0
	s_mov_b32 s24, -2
	v_mov_b32_e32 v1, v0
	v_mov_b32_e32 v2, v0
	v_mov_b32_e32 v3, v0
	v_mov_b32_e32 v6, v0
	s_waitcnt lgkmcnt(0)
	v_mov_b32_e32 v7, v0
	v_mov_b32_e32 v8, v0
	v_mov_b32_e32 v9, v0
	v_mov_b32_e32 v18, v0
	v_mov_b32_e32 v19, v0
	v_mov_b32_e32 v20, v0
	v_mov_b32_e32 v21, v0
	v_mov_b32_e32 v22, v0
	v_mov_b32_e32 v23, v0
	v_mov_b32_e32 v24, v0
	v_mov_b32_e32 v25, v0
	v_mov_b32_e32 v34, v0
	v_mov_b32_e32 v35, v0
	v_mov_b32_e32 v36, v0
	v_mov_b32_e32 v37, v0
	v_mov_b32_e32 v38, v0
	v_mov_b32_e32 v39, v0
	v_mov_b32_e32 v40, v0
	v_mov_b32_e32 v41, v0
	v_mov_b32_e32 v50, v0
	v_mov_b32_e32 v51, v0
	v_mov_b32_e32 v52, v0
	v_mov_b32_e32 v53, v0
	v_mov_b32_e32 v54, v0
	v_mov_b32_e32 v55, v0
	v_mov_b32_e32 v56, v0
	v_mov_b32_e32 v57, v0
	v_mov_b32_e32 v10, v0
	v_mov_b32_e32 v11, v0
	v_mov_b32_e32 v12, v0
	v_mov_b32_e32 v13, v0
	v_mov_b32_e32 v14, v0
	v_mov_b32_e32 v15, v0
	v_mov_b32_e32 v16, v0
	v_mov_b32_e32 v17, v0
	v_mov_b32_e32 v26, v0
	v_mov_b32_e32 v27, v0
	v_mov_b32_e32 v28, v0
	v_mov_b32_e32 v29, v0
	v_mov_b32_e32 v30, v0
	v_mov_b32_e32 v31, v0
	v_mov_b32_e32 v32, v0
	v_mov_b32_e32 v33, v0
	v_mov_b32_e32 v42, v0
	v_mov_b32_e32 v43, v0
	v_mov_b32_e32 v44, v0
	v_mov_b32_e32 v45, v0
	v_mov_b32_e32 v46, v0
	v_mov_b32_e32 v47, v0
	v_mov_b32_e32 v48, v0
	v_mov_b32_e32 v49, v0
	v_mov_b32_e32 v58, v0
	v_mov_b32_e32 v59, v0
	v_mov_b32_e32 v60, v0
	v_mov_b32_e32 v61, v0
	v_mov_b32_e32 v62, v0
	v_mov_b32_e32 v63, v0
	v_mov_b32_e32 v64, v0
	v_mov_b32_e32 v65, v0
	v_mov_b32_e32 v66, v0
	v_mov_b32_e32 v67, v0
	v_mov_b32_e32 v68, v0
	v_mov_b32_e32 v69, v0
	v_mov_b32_e32 v70, v0
	v_mov_b32_e32 v71, v0
	v_mov_b32_e32 v72, v0
	v_mov_b32_e32 v73, v0
	v_mov_b32_e32 v82, v0
	v_mov_b32_e32 v83, v0
	v_mov_b32_e32 v84, v0
	v_mov_b32_e32 v85, v0
	v_mov_b32_e32 v86, v0
	v_mov_b32_e32 v87, v0
	v_mov_b32_e32 v88, v0
	v_mov_b32_e32 v89, v0
	v_mov_b32_e32 v98, v0
	v_mov_b32_e32 v99, v0
	v_mov_b32_e32 v100, v0
	v_mov_b32_e32 v101, v0
	v_mov_b32_e32 v102, v0
	v_mov_b32_e32 v103, v0
	v_mov_b32_e32 v104, v0
	v_mov_b32_e32 v105, v0
	v_mov_b32_e32 v114, v0
	v_mov_b32_e32 v115, v0
	v_mov_b32_e32 v116, v0
	v_mov_b32_e32 v117, v0
	v_mov_b32_e32 v118, v0
	v_mov_b32_e32 v119, v0
	v_mov_b32_e32 v120, v0
	v_mov_b32_e32 v121, v0
	v_mov_b32_e32 v74, v0
	v_mov_b32_e32 v75, v0
	v_mov_b32_e32 v76, v0
	v_mov_b32_e32 v77, v0
	v_mov_b32_e32 v78, v0
	v_mov_b32_e32 v79, v0
	v_mov_b32_e32 v80, v0
	v_mov_b32_e32 v81, v0
	v_mov_b32_e32 v90, v0
	v_mov_b32_e32 v91, v0
	v_mov_b32_e32 v92, v0
	v_mov_b32_e32 v93, v0
	v_mov_b32_e32 v94, v0
	v_mov_b32_e32 v95, v0
	v_mov_b32_e32 v96, v0
	v_mov_b32_e32 v97, v0
	v_mov_b32_e32 v106, v0
	v_mov_b32_e32 v107, v0
	v_mov_b32_e32 v108, v0
	v_mov_b32_e32 v109, v0
	v_mov_b32_e32 v110, v0
	v_mov_b32_e32 v111, v0
	v_mov_b32_e32 v112, v0
	v_mov_b32_e32 v113, v0
	v_mov_b32_e32 v122, v0
	v_mov_b32_e32 v123, v0
	v_mov_b32_e32 v124, v0
	v_mov_b32_e32 v125, v0
	v_mov_b32_e32 v126, v0
	v_mov_b32_e32 v127, v0
	v_mov_b32_e32 v128, v0
	v_mov_b32_e32 v129, v0
	s_cmp_eq_u32 s37, 1
	s_cbranch_scc1 .LBB0_163
	s_add_u32 s0, s22, 0xfff80080
	s_addc_u32 s1, s23, -1
	s_add_i32 s3, 0, 0x10000
	s_cmp_eq_u32 s24, 28
	s_cselect_b32 s15, s79, s1
	s_cselect_b32 s14, s78, s0
	v_add_u32_e32 v162, s3, v145
	s_cselect_b32 s1, s2, s10
	s_cselect_b32 s0, s8, s9
	s_add_i32 s6, 0, 0x14000
	ds_read_b128 v[140:143], v162
	ds_read_b128 v[148:151], v162 offset:1024
	ds_read_b128 v[172:175], v162 offset:2048
	ds_read_b128 v[190:193], v162 offset:3072
	v_add_u32_e32 v162, s6, v145
	ds_read_b128 v[194:197], v162
	ds_read_b128 v[198:201], v162 offset:1024
	ds_read_b128 v[202:205], v162 offset:2048
	ds_read_b128 v[206:209], v162 offset:3072
	v_lshl_add_u64 v[162:163], s[22:23], 0, v[136:137]
	s_add_i32 m0, s26, 0xc000
	ds_read_b128 v[210:213], v147
	ds_read_b128 v[214:217], v147 offset:1024
	ds_read_b128 v[218:221], v147 offset:2048
	ds_read_b128 v[222:225], v147 offset:3072
	ds_read_b128 v[226:229], v147 offset:4096
	ds_read_b128 v[230:233], v147 offset:5120
	ds_read_b128 v[234:237], v147 offset:6144
	ds_read_b128 v[238:241], v147 offset:7168
	global_load_lds_dwordx4 v[162:163], off
	v_lshl_add_u64 v[162:163], s[22:23], 0, v[138:139]
	s_add_i32 m0, s26, 0xe000
	s_nop 0
	global_load_lds_dwordx4 v[162:163], off
	s_waitcnt vmcnt(24)
	s_waitcnt lgkmcnt(0)
	s_barrier
	s_setprio 1
	s_waitcnt lgkmcnt(0)
	v_mfma_f32_16x16x32_bf16 v[126:129], v[140:143], v[210:213], v[126:129]
	v_mfma_f32_16x16x32_bf16 v[122:125], v[172:175], v[210:213], v[122:125]
	v_mfma_f32_16x16x32_bf16 v[110:113], v[140:143], v[218:221], v[110:113]
	v_mfma_f32_16x16x32_bf16 v[106:109], v[172:175], v[218:221], v[106:109]
	v_mfma_f32_16x16x32_bf16 v[94:97], v[140:143], v[226:229], v[94:97]
	v_mfma_f32_16x16x32_bf16 v[90:93], v[172:175], v[226:229], v[90:93]
	v_mfma_f32_16x16x32_bf16 v[78:81], v[140:143], v[234:237], v[78:81]
	v_mfma_f32_16x16x32_bf16 v[74:77], v[172:175], v[234:237], v[74:77]
	v_mfma_f32_16x16x32_bf16 v[126:129], v[148:151], v[214:217], v[126:129]
	v_mfma_f32_16x16x32_bf16 v[122:125], v[190:193], v[214:217], v[122:125]
	v_mfma_f32_16x16x32_bf16 v[110:113], v[148:151], v[222:225], v[110:113]
	v_mfma_f32_16x16x32_bf16 v[106:109], v[190:193], v[222:225], v[106:109]
	v_mfma_f32_16x16x32_bf16 v[94:97], v[148:151], v[230:233], v[94:97]
	v_mfma_f32_16x16x32_bf16 v[90:93], v[190:193], v[230:233], v[90:93]
	v_mfma_f32_16x16x32_bf16 v[78:81], v[148:151], v[238:241], v[78:81]
	v_mfma_f32_16x16x32_bf16 v[74:77], v[190:193], v[238:241], v[74:77]
	s_setprio 0
	s_setprio 1
	v_mfma_f32_16x16x32_bf16 v[118:121], v[194:197], v[210:213], v[118:121]
	v_mfma_f32_16x16x32_bf16 v[114:117], v[202:205], v[210:213], v[114:117]
	v_mfma_f32_16x16x32_bf16 v[102:105], v[194:197], v[218:221], v[102:105]
	v_mfma_f32_16x16x32_bf16 v[98:101], v[202:205], v[218:221], v[98:101]
	v_mfma_f32_16x16x32_bf16 v[86:89], v[194:197], v[226:229], v[86:89]
	v_mfma_f32_16x16x32_bf16 v[82:85], v[202:205], v[226:229], v[82:85]
	v_mfma_f32_16x16x32_bf16 v[70:73], v[194:197], v[234:237], v[70:73]
	v_mfma_f32_16x16x32_bf16 v[66:69], v[202:205], v[234:237], v[66:69]
	v_mfma_f32_16x16x32_bf16 v[118:121], v[198:201], v[214:217], v[118:121]
	v_mfma_f32_16x16x32_bf16 v[114:117], v[206:209], v[214:217], v[114:117]
	v_mfma_f32_16x16x32_bf16 v[102:105], v[198:201], v[222:225], v[102:105]
	v_mfma_f32_16x16x32_bf16 v[98:101], v[206:209], v[222:225], v[98:101]
	v_mfma_f32_16x16x32_bf16 v[86:89], v[198:201], v[230:233], v[86:89]
	v_mfma_f32_16x16x32_bf16 v[82:85], v[206:209], v[230:233], v[82:85]
	v_mfma_f32_16x16x32_bf16 v[70:73], v[198:201], v[238:241], v[70:73]
	v_mfma_f32_16x16x32_bf16 v[66:69], v[206:209], v[238:241], v[66:69]
	s_setprio 0
	s_barrier
	s_add_i32 s3, s3, s11
	v_lshl_add_u64 v[162:163], s[0:1], 0, v[4:5]
	s_mov_b32 m0, s3
	ds_read_b128 v[210:213], v147 offset:16384
	ds_read_b128 v[214:217], v147 offset:17408
	ds_read_b128 v[218:221], v147 offset:18432
	ds_read_b128 v[222:225], v147 offset:19456
	ds_read_b128 v[226:229], v147 offset:20480
	ds_read_b128 v[230:233], v147 offset:21504
	ds_read_b128 v[234:237], v147 offset:22528
	ds_read_b128 v[238:241], v147 offset:23552
	global_load_lds_dwordx4 v[162:163], off
	s_add_i32 m0, s3, 0x2000
	s_add_u32 s4, s0, 0x80000
	v_lshl_add_u64 v[166:167], s[0:1], 0, v[130:131]
	s_addc_u32 s5, s1, 0
	s_add_i32 s3, s6, s11
	global_load_lds_dwordx4 v[166:167], off
	v_lshl_add_u64 v[176:177], s[4:5], 0, v[4:5]
	s_mov_b32 m0, s3
	v_lshl_add_u64 v[180:181], s[14:15], 0, v[132:133]
	global_load_lds_dwordx4 v[176:177], off
	v_lshl_add_u64 v[176:177], s[4:5], 0, v[130:131]
	s_add_i32 m0, s3, 0x2000
	s_nop 0
	global_load_lds_dwordx4 v[176:177], off
	v_lshl_add_u64 v[176:177], s[14:15], 0, v[134:135]
	s_mov_b32 m0, s26
	s_nop 0
	global_load_lds_dwordx4 v[176:177], off
	s_mov_b32 m0, s27
	s_nop 0
	global_load_lds_dwordx4 v[180:181], off
	s_waitcnt vmcnt(24)
	s_waitcnt lgkmcnt(0)
	s_barrier
	s_setprio 1
	s_waitcnt lgkmcnt(0)
	v_mfma_f32_16x16x32_bf16 v[62:65], v[140:143], v[210:213], v[62:65]
	v_mfma_f32_16x16x32_bf16 v[58:61], v[172:175], v[210:213], v[58:61]
	v_mfma_f32_16x16x32_bf16 v[46:49], v[140:143], v[218:221], v[46:49]
	v_mfma_f32_16x16x32_bf16 v[42:45], v[172:175], v[218:221], v[42:45]
	v_mfma_f32_16x16x32_bf16 v[30:33], v[140:143], v[226:229], v[30:33]
	v_mfma_f32_16x16x32_bf16 v[26:29], v[172:175], v[226:229], v[26:29]
	v_mfma_f32_16x16x32_bf16 v[14:17], v[140:143], v[234:237], v[14:17]
	v_mfma_f32_16x16x32_bf16 v[10:13], v[172:175], v[234:237], v[10:13]
	v_mfma_f32_16x16x32_bf16 v[62:65], v[148:151], v[214:217], v[62:65]
	v_mfma_f32_16x16x32_bf16 v[58:61], v[190:193], v[214:217], v[58:61]
	v_mfma_f32_16x16x32_bf16 v[46:49], v[148:151], v[222:225], v[46:49]
	v_mfma_f32_16x16x32_bf16 v[42:45], v[190:193], v[222:225], v[42:45]
	v_mfma_f32_16x16x32_bf16 v[30:33], v[148:151], v[230:233], v[30:33]
	v_mfma_f32_16x16x32_bf16 v[26:29], v[190:193], v[230:233], v[26:29]
	v_mfma_f32_16x16x32_bf16 v[14:17], v[148:151], v[238:241], v[14:17]
	v_mfma_f32_16x16x32_bf16 v[10:13], v[190:193], v[238:241], v[10:13]
	s_setprio 0
	s_setprio 1
	v_mfma_f32_16x16x32_bf16 v[54:57], v[194:197], v[210:213], v[54:57]
	v_mfma_f32_16x16x32_bf16 v[50:53], v[202:205], v[210:213], v[50:53]
	v_mfma_f32_16x16x32_bf16 v[38:41], v[194:197], v[218:221], v[38:41]
	v_mfma_f32_16x16x32_bf16 v[34:37], v[202:205], v[218:221], v[34:37]
	v_mfma_f32_16x16x32_bf16 v[22:25], v[194:197], v[226:229], v[22:25]
	v_mfma_f32_16x16x32_bf16 v[18:21], v[202:205], v[226:229], v[18:21]
	v_mfma_f32_16x16x32_bf16 v[6:9], v[194:197], v[234:237], v[6:9]
	v_mfma_f32_16x16x32_bf16 v[0:3], v[202:205], v[234:237], v[0:3]
	v_mfma_f32_16x16x32_bf16 v[54:57], v[198:201], v[214:217], v[54:57]
	v_mfma_f32_16x16x32_bf16 v[50:53], v[206:209], v[214:217], v[50:53]
	v_mfma_f32_16x16x32_bf16 v[38:41], v[198:201], v[222:225], v[38:41]
	v_mfma_f32_16x16x32_bf16 v[34:37], v[206:209], v[222:225], v[34:37]
	v_mfma_f32_16x16x32_bf16 v[22:25], v[198:201], v[230:233], v[22:25]
	v_mfma_f32_16x16x32_bf16 v[18:21], v[206:209], v[230:233], v[18:21]
	v_mfma_f32_16x16x32_bf16 v[6:9], v[198:201], v[238:241], v[6:9]
	v_mfma_f32_16x16x32_bf16 v[0:3], v[206:209], v[238:241], v[0:3]
	s_setprio 0
	s_barrier
	s_branch .Lpeelmid_163

.Lpeelmid_163:
	s_add_i32 s3, 0, 0x18000
	v_add_u32_e32 v164, s3, v145
	s_add_i32 s6, 0, 0x1c000
	ds_read_b128 v[140:143], v164
	ds_read_b128 v[148:151], v164 offset:1024
	ds_read_b128 v[172:175], v164 offset:2048
	ds_read_b128 v[190:193], v164 offset:3072
	v_add_u32_e32 v164, s6, v145
	ds_read_b128 v[194:197], v164
	ds_read_b128 v[198:201], v164 offset:1024
	ds_read_b128 v[202:205], v164 offset:2048
	ds_read_b128 v[206:209], v164 offset:3072
	s_add_u32 s4, s14, 0x80000
	s_addc_u32 s5, s15, 0
	s_mov_b32 m0, s30
	v_lshl_add_u64 v[242:243], s[4:5], 0, v[134:135]
	ds_read_b128 v[210:213], v147 offset:32768
	ds_read_b128 v[214:217], v147 offset:33792
	ds_read_b128 v[218:221], v147 offset:34816
	ds_read_b128 v[222:225], v147 offset:35840
	ds_read_b128 v[226:229], v147 offset:36864
	ds_read_b128 v[230:233], v147 offset:37888
	ds_read_b128 v[234:237], v147 offset:38912
	ds_read_b128 v[238:241], v147 offset:39936
	global_load_lds_dwordx4 v[242:243], off
	v_lshl_add_u64 v[242:243], s[4:5], 0, v[132:133]
	s_mov_b32 m0, s31
	s_nop 0
	global_load_lds_dwordx4 v[242:243], off
	s_waitcnt vmcnt(8)
	s_waitcnt lgkmcnt(0)
	s_barrier
	s_setprio 1
	s_waitcnt lgkmcnt(0)
	v_mfma_f32_16x16x32_bf16 v[126:129], v[140:143], v[210:213], v[126:129]
	v_mfma_f32_16x16x32_bf16 v[122:125], v[172:175], v[210:213], v[122:125]
	v_mfma_f32_16x16x32_bf16 v[110:113], v[140:143], v[218:221], v[110:113]
	v_mfma_f32_16x16x32_bf16 v[106:109], v[172:175], v[218:221], v[106:109]
	v_mfma_f32_16x16x32_bf16 v[94:97], v[140:143], v[226:229], v[94:97]
	v_mfma_f32_16x16x32_bf16 v[90:93], v[172:175], v[226:229], v[90:93]
	v_mfma_f32_16x16x32_bf16 v[78:81], v[140:143], v[234:237], v[78:81]
	v_mfma_f32_16x16x32_bf16 v[74:77], v[172:175], v[234:237], v[74:77]
	v_mfma_f32_16x16x32_bf16 v[126:129], v[148:151], v[214:217], v[126:129]
	v_mfma_f32_16x16x32_bf16 v[122:125], v[190:193], v[214:217], v[122:125]
	v_mfma_f32_16x16x32_bf16 v[110:113], v[148:151], v[222:225], v[110:113]
	v_mfma_f32_16x16x32_bf16 v[106:109], v[190:193], v[222:225], v[106:109]
	v_mfma_f32_16x16x32_bf16 v[94:97], v[148:151], v[230:233], v[94:97]
	v_mfma_f32_16x16x32_bf16 v[90:93], v[190:193], v[230:233], v[90:93]
	v_mfma_f32_16x16x32_bf16 v[78:81], v[148:151], v[238:241], v[78:81]
	v_mfma_f32_16x16x32_bf16 v[74:77], v[190:193], v[238:241], v[74:77]
	s_setprio 0
	s_setprio 1
	v_mfma_f32_16x16x32_bf16 v[118:121], v[194:197], v[210:213], v[118:121]
	v_mfma_f32_16x16x32_bf16 v[114:117], v[202:205], v[210:213], v[114:117]
	v_mfma_f32_16x16x32_bf16 v[102:105], v[194:197], v[218:221], v[102:105]
	v_mfma_f32_16x16x32_bf16 v[98:101], v[202:205], v[218:221], v[98:101]
	v_mfma_f32_16x16x32_bf16 v[86:89], v[194:197], v[226:229], v[86:89]
	v_mfma_f32_16x16x32_bf16 v[82:85], v[202:205], v[226:229], v[82:85]
	v_mfma_f32_16x16x32_bf16 v[70:73], v[194:197], v[234:237], v[70:73]
	v_mfma_f32_16x16x32_bf16 v[66:69], v[202:205], v[234:237], v[66:69]
	v_mfma_f32_16x16x32_bf16 v[118:121], v[198:201], v[214:217], v[118:121]
	v_mfma_f32_16x16x32_bf16 v[114:117], v[206:209], v[214:217], v[114:117]
	v_mfma_f32_16x16x32_bf16 v[102:105], v[198:201], v[222:225], v[102:105]
	v_mfma_f32_16x16x32_bf16 v[98:101], v[206:209], v[222:225], v[98:101]
	v_mfma_f32_16x16x32_bf16 v[86:89], v[198:201], v[230:233], v[86:89]
	v_mfma_f32_16x16x32_bf16 v[82:85], v[206:209], v[230:233], v[82:85]
	v_mfma_f32_16x16x32_bf16 v[70:73], v[198:201], v[238:241], v[70:73]
	v_mfma_f32_16x16x32_bf16 v[66:69], v[206:209], v[238:241], v[66:69]
	s_setprio 0
	s_barrier
	s_add_i32 s3, s3, s11
	v_lshl_add_u64 v[162:163], v[162:163], 0, s[70:71]
	s_mov_b32 m0, s3
	ds_read_b128 v[210:213], v147 offset:49152
	ds_read_b128 v[214:217], v147 offset:50176
	ds_read_b128 v[218:221], v147 offset:51200
	ds_read_b128 v[222:225], v147 offset:52224
	ds_read_b128 v[226:229], v147 offset:53248
	ds_read_b128 v[230:233], v147 offset:54272
	ds_read_b128 v[234:237], v147 offset:55296
	ds_read_b128 v[238:241], v147 offset:56320
	global_load_lds_dwordx4 v[162:163], off
	s_add_i32 m0, s3, 0x2000
	s_add_u32 s0, s0, 0x80080
	v_lshl_add_u64 v[162:163], v[166:167], 0, s[70:71]
	s_addc_u32 s1, s1, 0
	s_add_i32 s3, s6, s11
	global_load_lds_dwordx4 v[162:163], off
	v_lshl_add_u64 v[162:163], s[0:1], 0, v[4:5]
	s_mov_b32 m0, s3
	s_nop 0
	global_load_lds_dwordx4 v[162:163], off
	v_lshl_add_u64 v[162:163], s[0:1], 0, v[130:131]
	s_add_i32 m0, s3, 0x2000
	s_nop 0
	global_load_lds_dwordx4 v[162:163], off
	v_lshl_add_u64 v[162:163], v[176:177], 0, s[70:71]
	s_mov_b32 m0, s35
	s_nop 0
	global_load_lds_dwordx4 v[162:163], off
	v_lshl_add_u64 v[162:163], v[180:181], 0, s[70:71]
	s_mov_b32 m0, s36
	s_nop 0
	global_load_lds_dwordx4 v[162:163], off
	s_waitcnt vmcnt(8)
	s_waitcnt lgkmcnt(0)
	s_barrier
	s_setprio 1
	s_waitcnt lgkmcnt(0)
	v_mfma_f32_16x16x32_bf16 v[62:65], v[140:143], v[210:213], v[62:65]
	v_mfma_f32_16x16x32_bf16 v[58:61], v[172:175], v[210:213], v[58:61]
	v_mfma_f32_16x16x32_bf16 v[46:49], v[140:143], v[218:221], v[46:49]
	v_mfma_f32_16x16x32_bf16 v[42:45], v[172:175], v[218:221], v[42:45]
	v_mfma_f32_16x16x32_bf16 v[30:33], v[140:143], v[226:229], v[30:33]
	v_mfma_f32_16x16x32_bf16 v[26:29], v[172:175], v[226:229], v[26:29]
	v_mfma_f32_16x16x32_bf16 v[14:17], v[140:143], v[234:237], v[14:17]
	v_mfma_f32_16x16x32_bf16 v[10:13], v[172:175], v[234:237], v[10:13]
	v_mfma_f32_16x16x32_bf16 v[62:65], v[148:151], v[214:217], v[62:65]
	v_mfma_f32_16x16x32_bf16 v[58:61], v[190:193], v[214:217], v[58:61]
	v_mfma_f32_16x16x32_bf16 v[46:49], v[148:151], v[222:225], v[46:49]
	v_mfma_f32_16x16x32_bf16 v[42:45], v[190:193], v[222:225], v[42:45]
	v_mfma_f32_16x16x32_bf16 v[30:33], v[148:151], v[230:233], v[30:33]
	v_mfma_f32_16x16x32_bf16 v[26:29], v[190:193], v[230:233], v[26:29]
	v_mfma_f32_16x16x32_bf16 v[14:17], v[148:151], v[238:241], v[14:17]
	v_mfma_f32_16x16x32_bf16 v[10:13], v[190:193], v[238:241], v[10:13]
	s_setprio 0
	s_setprio 1
	v_mfma_f32_16x16x32_bf16 v[54:57], v[194:197], v[210:213], v[54:57]
	v_mfma_f32_16x16x32_bf16 v[50:53], v[202:205], v[210:213], v[50:53]
	v_mfma_f32_16x16x32_bf16 v[38:41], v[194:197], v[218:221], v[38:41]
	v_mfma_f32_16x16x32_bf16 v[34:37], v[202:205], v[218:221], v[34:37]
	v_mfma_f32_16x16x32_bf16 v[22:25], v[194:197], v[226:229], v[22:25]
	v_mfma_f32_16x16x32_bf16 v[18:21], v[202:205], v[226:229], v[18:21]
	v_mfma_f32_16x16x32_bf16 v[6:9], v[194:197], v[234:237], v[6:9]
	v_mfma_f32_16x16x32_bf16 v[0:3], v[202:205], v[234:237], v[0:3]
	v_mfma_f32_16x16x32_bf16 v[54:57], v[198:201], v[214:217], v[54:57]
	v_mfma_f32_16x16x32_bf16 v[50:53], v[206:209], v[214:217], v[50:53]
	v_mfma_f32_16x16x32_bf16 v[38:41], v[198:201], v[222:225], v[38:41]
	v_mfma_f32_16x16x32_bf16 v[34:37], v[206:209], v[222:225], v[34:37]
	v_mfma_f32_16x16x32_bf16 v[22:25], v[198:201], v[230:233], v[22:25]
	v_mfma_f32_16x16x32_bf16 v[18:21], v[206:209], v[230:233], v[18:21]
	v_mfma_f32_16x16x32_bf16 v[6:9], v[198:201], v[238:241], v[6:9]
	v_mfma_f32_16x16x32_bf16 v[0:3], v[206:209], v[238:241], v[0:3]
	s_setprio 0
	s_barrier
	s_add_i32 s24, s24, 2
	s_add_u32 s22, s22, 0x100
	s_addc_u32 s23, s23, 0
	s_add_u32 s9, s9, 0x100
	s_addc_u32 s10, s10, 0
	s_cmp_gt_u32 s24, 29
	s_cbranch_scc0 .LBB0_163
	s_and_b64 vcc, exec, s[46:47]
	s_cbranch_vccz .LBB0_166
	s_barrier

.LBB0_204:
	s_ashr_i32 s49, s48, 31
	s_lshl_b64 s[2:3], s[48:49], 19
	v_readlane_b32 s4, v253, 17
	v_readlane_b32 s5, v253, 18
	s_add_u32 s84, s4, s2
	s_addc_u32 s85, s5, s3
	s_and_b64 s[2:3], s[42:43], exec
	s_cselect_b32 s2, s85, s15
	s_cselect_b32 s8, s84, s14
	s_add_u32 s22, s0, 0x40080
	s_addc_u32 s23, s1, 0
	s_add_u32 s9, s14, 0x100
	v_mov_b32_e32 v0, 0
	s_addc_u32 s10, s15, 0
	s_mov_b32 s24, -2
	v_mov_b32_e32 v1, v0
	v_mov_b32_e32 v2, v0
	v_mov_b32_e32 v3, v0
	v_mov_b32_e32 v6, v0
	v_mov_b32_e32 v7, v0
	v_mov_b32_e32 v8, v0
	v_mov_b32_e32 v9, v0
	v_mov_b32_e32 v10, v0
	v_mov_b32_e32 v11, v0
	v_mov_b32_e32 v12, v0
	v_mov_b32_e32 v13, v0
	v_mov_b32_e32 v14, v0
	v_mov_b32_e32 v15, v0
	v_mov_b32_e32 v16, v0
	v_mov_b32_e32 v17, v0
	v_mov_b32_e32 v18, v0
	v_mov_b32_e32 v19, v0
	v_mov_b32_e32 v20, v0
	v_mov_b32_e32 v21, v0
	v_mov_b32_e32 v22, v0
	v_mov_b32_e32 v23, v0
	v_mov_b32_e32 v24, v0
	v_mov_b32_e32 v25, v0
	v_mov_b32_e32 v26, v0
	v_mov_b32_e32 v27, v0
	v_mov_b32_e32 v28, v0
	v_mov_b32_e32 v29, v0
	v_mov_b32_e32 v30, v0
	v_mov_b32_e32 v31, v0
	v_mov_b32_e32 v32, v0
	v_mov_b32_e32 v33, v0
	v_mov_b32_e32 v66, v0
	v_mov_b32_e32 v67, v0
	v_mov_b32_e32 v68, v0
	v_mov_b32_e32 v69, v0
	v_mov_b32_e32 v70, v0
	v_mov_b32_e32 v71, v0
	v_mov_b32_e32 v72, v0
	v_mov_b32_e32 v73, v0
	v_mov_b32_e32 v74, v0
	v_mov_b32_e32 v75, v0
	v_mov_b32_e32 v76, v0
	v_mov_b32_e32 v77, v0
	v_mov_b32_e32 v78, v0
	v_mov_b32_e32 v79, v0
	v_mov_b32_e32 v80, v0
	v_mov_b32_e32 v81, v0
	v_mov_b32_e32 v82, v0
	v_mov_b32_e32 v83, v0
	v_mov_b32_e32 v84, v0
	v_mov_b32_e32 v85, v0
	v_mov_b32_e32 v86, v0
	v_mov_b32_e32 v87, v0
	v_mov_b32_e32 v88, v0
	v_mov_b32_e32 v89, v0
	v_mov_b32_e32 v90, v0
	v_mov_b32_e32 v91, v0
	v_mov_b32_e32 v92, v0
	v_mov_b32_e32 v93, v0
	v_mov_b32_e32 v94, v0
	v_mov_b32_e32 v95, v0
	v_mov_b32_e32 v96, v0
	v_mov_b32_e32 v97, v0
	v_mov_b32_e32 v34, v0
	v_mov_b32_e32 v35, v0
	v_mov_b32_e32 v36, v0
	v_mov_b32_e32 v37, v0
	v_mov_b32_e32 v38, v0
	v_mov_b32_e32 v39, v0
	v_mov_b32_e32 v40, v0
	v_mov_b32_e32 v41, v0
	v_mov_b32_e32 v42, v0
	v_mov_b32_e32 v43, v0
	v_mov_b32_e32 v44, v0
	v_mov_b32_e32 v45, v0
	v_mov_b32_e32 v46, v0
	v_mov_b32_e32 v47, v0
	v_mov_b32_e32 v48, v0
	v_mov_b32_e32 v49, v0
	v_mov_b32_e32 v50, v0
	v_mov_b32_e32 v51, v0
	v_mov_b32_e32 v52, v0
	v_mov_b32_e32 v53, v0
	v_mov_b32_e32 v54, v0
	v_mov_b32_e32 v55, v0
	v_mov_b32_e32 v56, v0
	v_mov_b32_e32 v57, v0
	v_mov_b32_e32 v58, v0
	v_mov_b32_e32 v59, v0
	v_mov_b32_e32 v60, v0
	v_mov_b32_e32 v61, v0
	v_mov_b32_e32 v62, v0
	v_mov_b32_e32 v63, v0
	v_mov_b32_e32 v64, v0
	v_mov_b32_e32 v65, v0
	v_mov_b32_e32 v98, v0
	v_mov_b32_e32 v99, v0
	v_mov_b32_e32 v100, v0
	v_mov_b32_e32 v101, v0
	v_mov_b32_e32 v102, v0
	v_mov_b32_e32 v103, v0
	v_mov_b32_e32 v104, v0
	v_mov_b32_e32 v105, v0
	v_mov_b32_e32 v106, v0
	v_mov_b32_e32 v107, v0
	v_mov_b32_e32 v108, v0
	v_mov_b32_e32 v109, v0
	v_mov_b32_e32 v110, v0
	v_mov_b32_e32 v111, v0
	v_mov_b32_e32 v112, v0
	v_mov_b32_e32 v113, v0
	v_mov_b32_e32 v114, v0
	v_mov_b32_e32 v115, v0
	v_mov_b32_e32 v116, v0
	v_mov_b32_e32 v117, v0
	v_mov_b32_e32 v118, v0
	v_mov_b32_e32 v119, v0
	v_mov_b32_e32 v120, v0
	v_mov_b32_e32 v121, v0
	v_mov_b32_e32 v122, v0
	v_mov_b32_e32 v123, v0
	v_mov_b32_e32 v124, v0
	v_mov_b32_e32 v125, v0
	v_mov_b32_e32 v126, v0
	v_mov_b32_e32 v127, v0
	v_mov_b32_e32 v128, v0
	v_mov_b32_e32 v129, v0
	s_cmp_eq_u32 s37, 1
	s_cbranch_scc1 .LBB0_205
	s_add_u32 s0, s22, 0xfffc0080
	s_addc_u32 s1, s23, -1
	s_add_i32 s3, 0, 0x10000
	s_cmp_eq_u32 s24, 12
	s_cselect_b32 s15, s83, s1
	s_cselect_b32 s14, s82, s0
	v_add_u32_e32 v144, s3, v168
	s_cselect_b32 s1, s2, s10
	s_cselect_b32 s0, s8, s9
	s_add_i32 s6, 0, 0x14000
	ds_read_b128 v[140:143], v144
	ds_read_b128 v[174:177], v144 offset:1024
	ds_read_b128 v[190:193], v144 offset:2048
	ds_read_b128 v[194:197], v144 offset:3072
	v_add_u32_e32 v144, s6, v168
	ds_read_b128 v[198:201], v144
	ds_read_b128 v[202:205], v144 offset:1024
	ds_read_b128 v[206:209], v144 offset:2048
	ds_read_b128 v[210:213], v144 offset:3072
	v_lshl_add_u64 v[144:145], s[22:23], 0, v[136:137]
	s_add_i32 m0, s27, 0xc000
	ds_read_b128 v[214:217], v172
	ds_read_b128 v[218:221], v172 offset:1024
	ds_read_b128 v[222:225], v172 offset:2048
	ds_read_b128 v[226:229], v172 offset:3072
	ds_read_b128 v[230:233], v172 offset:4096
	ds_read_b128 v[234:237], v172 offset:5120
	ds_read_b128 v[238:241], v172 offset:6144
	ds_read_b128 v[242:245], v172 offset:7168
	global_load_lds_dwordx4 v[144:145], off
	v_lshl_add_u64 v[144:145], s[22:23], 0, v[138:139]
	s_add_i32 m0, s27, 0xe000
	s_nop 0
	global_load_lds_dwordx4 v[144:145], off
	s_waitcnt vmcnt(24)
	s_waitcnt lgkmcnt(0)
	s_barrier
	s_setprio 1
	s_waitcnt lgkmcnt(0)
	v_mfma_f32_16x16x32_bf16 v[126:129], v[140:143], v[214:217], v[126:129]
	v_mfma_f32_16x16x32_bf16 v[122:125], v[190:193], v[214:217], v[122:125]
	v_mfma_f32_16x16x32_bf16 v[118:121], v[140:143], v[222:225], v[118:121]
	v_mfma_f32_16x16x32_bf16 v[114:117], v[190:193], v[222:225], v[114:117]
	v_mfma_f32_16x16x32_bf16 v[110:113], v[140:143], v[230:233], v[110:113]
	v_mfma_f32_16x16x32_bf16 v[106:109], v[190:193], v[230:233], v[106:109]
	v_mfma_f32_16x16x32_bf16 v[102:105], v[140:143], v[238:241], v[102:105]
	v_mfma_f32_16x16x32_bf16 v[98:101], v[190:193], v[238:241], v[98:101]
	v_mfma_f32_16x16x32_bf16 v[126:129], v[174:177], v[218:221], v[126:129]
	v_mfma_f32_16x16x32_bf16 v[122:125], v[194:197], v[218:221], v[122:125]
	v_mfma_f32_16x16x32_bf16 v[118:121], v[174:177], v[226:229], v[118:121]
	v_mfma_f32_16x16x32_bf16 v[114:117], v[194:197], v[226:229], v[114:117]
	v_mfma_f32_16x16x32_bf16 v[110:113], v[174:177], v[234:237], v[110:113]
	v_mfma_f32_16x16x32_bf16 v[106:109], v[194:197], v[234:237], v[106:109]
	v_mfma_f32_16x16x32_bf16 v[102:105], v[174:177], v[242:245], v[102:105]
	v_mfma_f32_16x16x32_bf16 v[98:101], v[194:197], v[242:245], v[98:101]
	s_setprio 0
	s_setprio 1
	v_mfma_f32_16x16x32_bf16 v[62:65], v[198:201], v[214:217], v[62:65]
	v_mfma_f32_16x16x32_bf16 v[58:61], v[206:209], v[214:217], v[58:61]
	v_mfma_f32_16x16x32_bf16 v[54:57], v[198:201], v[222:225], v[54:57]
	v_mfma_f32_16x16x32_bf16 v[50:53], v[206:209], v[222:225], v[50:53]
	v_mfma_f32_16x16x32_bf16 v[46:49], v[198:201], v[230:233], v[46:49]
	v_mfma_f32_16x16x32_bf16 v[42:45], v[206:209], v[230:233], v[42:45]
	v_mfma_f32_16x16x32_bf16 v[38:41], v[198:201], v[238:241], v[38:41]
	v_mfma_f32_16x16x32_bf16 v[34:37], v[206:209], v[238:241], v[34:37]
	v_mfma_f32_16x16x32_bf16 v[62:65], v[202:205], v[218:221], v[62:65]
	v_mfma_f32_16x16x32_bf16 v[58:61], v[210:213], v[218:221], v[58:61]
	v_mfma_f32_16x16x32_bf16 v[54:57], v[202:205], v[226:229], v[54:57]
	v_mfma_f32_16x16x32_bf16 v[50:53], v[210:213], v[226:229], v[50:53]
	v_mfma_f32_16x16x32_bf16 v[46:49], v[202:205], v[234:237], v[46:49]
	v_mfma_f32_16x16x32_bf16 v[42:45], v[210:213], v[234:237], v[42:45]
	v_mfma_f32_16x16x32_bf16 v[38:41], v[202:205], v[242:245], v[38:41]
	v_mfma_f32_16x16x32_bf16 v[34:37], v[210:213], v[242:245], v[34:37]
	s_setprio 0
	s_barrier
	s_add_i32 s3, s3, s26
	v_lshl_add_u64 v[144:145], s[0:1], 0, v[4:5]
	s_mov_b32 m0, s3
	ds_read_b128 v[214:217], v172 offset:16384
	ds_read_b128 v[218:221], v172 offset:17408
	ds_read_b128 v[222:225], v172 offset:18432
	ds_read_b128 v[226:229], v172 offset:19456
	ds_read_b128 v[230:233], v172 offset:20480
	ds_read_b128 v[234:237], v172 offset:21504
	ds_read_b128 v[238:241], v172 offset:22528
	ds_read_b128 v[242:245], v172 offset:23552
	global_load_lds_dwordx4 v[144:145], off
	s_add_i32 m0, s3, 0x2000
	s_add_u32 s4, s0, 0x40000
	v_lshl_add_u64 v[246:247], s[0:1], 0, v[134:135]
	s_addc_u32 s5, s1, 0
	s_add_i32 s3, s6, s26
	global_load_lds_dwordx4 v[246:247], off
	v_lshl_add_u64 v[248:249], s[4:5], 0, v[4:5]
	s_mov_b32 m0, s3
	v_lshl_add_u64 v[250:251], s[14:15], 0, v[132:133]
	global_load_lds_dwordx4 v[248:249], off
	v_lshl_add_u64 v[248:249], s[4:5], 0, v[134:135]
	s_add_i32 m0, s3, 0x2000
	s_nop 0
	global_load_lds_dwordx4 v[248:249], off
	v_lshl_add_u64 v[248:249], s[14:15], 0, v[130:131]
	s_mov_b32 m0, s27
	s_nop 0
	global_load_lds_dwordx4 v[248:249], off
	s_mov_b32 m0, s30
	s_nop 0
	global_load_lds_dwordx4 v[250:251], off
	s_waitcnt vmcnt(24)
	s_waitcnt lgkmcnt(0)
	s_barrier
	s_setprio 1
	s_waitcnt lgkmcnt(0)
	v_mfma_f32_16x16x32_bf16 v[94:97], v[140:143], v[214:217], v[94:97]
	v_mfma_f32_16x16x32_bf16 v[90:93], v[190:193], v[214:217], v[90:93]
	v_mfma_f32_16x16x32_bf16 v[86:89], v[140:143], v[222:225], v[86:89]
	v_mfma_f32_16x16x32_bf16 v[82:85], v[190:193], v[222:225], v[82:85]
	v_mfma_f32_16x16x32_bf16 v[78:81], v[140:143], v[230:233], v[78:81]
	v_mfma_f32_16x16x32_bf16 v[74:77], v[190:193], v[230:233], v[74:77]
	v_mfma_f32_16x16x32_bf16 v[70:73], v[140:143], v[238:241], v[70:73]
	v_mfma_f32_16x16x32_bf16 v[66:69], v[190:193], v[238:241], v[66:69]
	v_mfma_f32_16x16x32_bf16 v[94:97], v[174:177], v[218:221], v[94:97]
	v_mfma_f32_16x16x32_bf16 v[90:93], v[194:197], v[218:221], v[90:93]
	v_mfma_f32_16x16x32_bf16 v[86:89], v[174:177], v[226:229], v[86:89]
	v_mfma_f32_16x16x32_bf16 v[82:85], v[194:197], v[226:229], v[82:85]
	v_mfma_f32_16x16x32_bf16 v[78:81], v[174:177], v[234:237], v[78:81]
	v_mfma_f32_16x16x32_bf16 v[74:77], v[194:197], v[234:237], v[74:77]
	v_mfma_f32_16x16x32_bf16 v[70:73], v[174:177], v[242:245], v[70:73]
	v_mfma_f32_16x16x32_bf16 v[66:69], v[194:197], v[242:245], v[66:69]
	s_setprio 0
	s_setprio 1
	v_mfma_f32_16x16x32_bf16 v[30:33], v[198:201], v[214:217], v[30:33]
	v_mfma_f32_16x16x32_bf16 v[26:29], v[206:209], v[214:217], v[26:29]
	v_mfma_f32_16x16x32_bf16 v[22:25], v[198:201], v[222:225], v[22:25]
	v_mfma_f32_16x16x32_bf16 v[18:21], v[206:209], v[222:225], v[18:21]
	v_mfma_f32_16x16x32_bf16 v[14:17], v[198:201], v[230:233], v[14:17]
	v_mfma_f32_16x16x32_bf16 v[10:13], v[206:209], v[230:233], v[10:13]
	v_mfma_f32_16x16x32_bf16 v[6:9], v[198:201], v[238:241], v[6:9]
	v_mfma_f32_16x16x32_bf16 v[0:3], v[206:209], v[238:241], v[0:3]
	v_mfma_f32_16x16x32_bf16 v[30:33], v[202:205], v[218:221], v[30:33]
	v_mfma_f32_16x16x32_bf16 v[26:29], v[210:213], v[218:221], v[26:29]
	v_mfma_f32_16x16x32_bf16 v[22:25], v[202:205], v[226:229], v[22:25]
	v_mfma_f32_16x16x32_bf16 v[18:21], v[210:213], v[226:229], v[18:21]
	v_mfma_f32_16x16x32_bf16 v[14:17], v[202:205], v[234:237], v[14:17]
	v_mfma_f32_16x16x32_bf16 v[10:13], v[210:213], v[234:237], v[10:13]
	v_mfma_f32_16x16x32_bf16 v[6:9], v[202:205], v[242:245], v[6:9]
	v_mfma_f32_16x16x32_bf16 v[0:3], v[210:213], v[242:245], v[0:3]
	s_setprio 0
	s_barrier
	s_branch .Lpeelmid_205

.Lpeelmid_205:
	s_add_i32 s3, 0, 0x18000
	v_add_u32_e32 v173, s3, v168
	s_add_i32 s6, 0, 0x1c000
	ds_read_b128 v[140:143], v173
	ds_read_b128 v[174:177], v173 offset:1024
	ds_read_b128 v[190:193], v173 offset:2048
	ds_read_b128 v[194:197], v173 offset:3072
	v_add_u32_e32 v173, s6, v168
	ds_read_b128 v[198:201], v173
	ds_read_b128 v[202:205], v173 offset:1024
	ds_read_b128 v[206:209], v173 offset:2048
	ds_read_b128 v[210:213], v173 offset:3072
	s_add_u32 s4, s14, 0x40000
	s_addc_u32 s5, s15, 0
	s_mov_b32 m0, s31
	v_lshl_add_u64 v[180:181], s[4:5], 0, v[130:131]
	ds_read_b128 v[214:217], v172 offset:32768
	ds_read_b128 v[218:221], v172 offset:33792
	ds_read_b128 v[222:225], v172 offset:34816
	ds_read_b128 v[226:229], v172 offset:35840
	ds_read_b128 v[230:233], v172 offset:36864
	ds_read_b128 v[234:237], v172 offset:37888
	ds_read_b128 v[238:241], v172 offset:38912
	ds_read_b128 v[242:245], v172 offset:39936
	global_load_lds_dwordx4 v[180:181], off
	v_lshl_add_u64 v[180:181], s[4:5], 0, v[132:133]
	s_mov_b32 m0, s34
	s_nop 0
	global_load_lds_dwordx4 v[180:181], off
	s_waitcnt vmcnt(8)
	s_waitcnt lgkmcnt(0)
	s_barrier
	s_setprio 1
	s_waitcnt lgkmcnt(0)
	v_mfma_f32_16x16x32_bf16 v[126:129], v[140:143], v[214:217], v[126:129]
	v_mfma_f32_16x16x32_bf16 v[122:125], v[190:193], v[214:217], v[122:125]
	v_mfma_f32_16x16x32_bf16 v[118:121], v[140:143], v[222:225], v[118:121]
	v_mfma_f32_16x16x32_bf16 v[114:117], v[190:193], v[222:225], v[114:117]
	v_mfma_f32_16x16x32_bf16 v[110:113], v[140:143], v[230:233], v[110:113]
	v_mfma_f32_16x16x32_bf16 v[106:109], v[190:193], v[230:233], v[106:109]
	v_mfma_f32_16x16x32_bf16 v[102:105], v[140:143], v[238:241], v[102:105]
	v_mfma_f32_16x16x32_bf16 v[98:101], v[190:193], v[238:241], v[98:101]
	v_mfma_f32_16x16x32_bf16 v[126:129], v[174:177], v[218:221], v[126:129]
	v_mfma_f32_16x16x32_bf16 v[122:125], v[194:197], v[218:221], v[122:125]
	v_mfma_f32_16x16x32_bf16 v[118:121], v[174:177], v[226:229], v[118:121]
	v_mfma_f32_16x16x32_bf16 v[114:117], v[194:197], v[226:229], v[114:117]
	v_mfma_f32_16x16x32_bf16 v[110:113], v[174:177], v[234:237], v[110:113]
	v_mfma_f32_16x16x32_bf16 v[106:109], v[194:197], v[234:237], v[106:109]
	v_mfma_f32_16x16x32_bf16 v[102:105], v[174:177], v[242:245], v[102:105]
	v_mfma_f32_16x16x32_bf16 v[98:101], v[194:197], v[242:245], v[98:101]
	s_setprio 0
	s_setprio 1
	v_mfma_f32_16x16x32_bf16 v[62:65], v[198:201], v[214:217], v[62:65]
	v_mfma_f32_16x16x32_bf16 v[58:61], v[206:209], v[214:217], v[58:61]
	v_mfma_f32_16x16x32_bf16 v[54:57], v[198:201], v[222:225], v[54:57]
	v_mfma_f32_16x16x32_bf16 v[50:53], v[206:209], v[222:225], v[50:53]
	v_mfma_f32_16x16x32_bf16 v[46:49], v[198:201], v[230:233], v[46:49]
	v_mfma_f32_16x16x32_bf16 v[42:45], v[206:209], v[230:233], v[42:45]
	v_mfma_f32_16x16x32_bf16 v[38:41], v[198:201], v[238:241], v[38:41]
	v_mfma_f32_16x16x32_bf16 v[34:37], v[206:209], v[238:241], v[34:37]
	v_mfma_f32_16x16x32_bf16 v[62:65], v[202:205], v[218:221], v[62:65]
	v_mfma_f32_16x16x32_bf16 v[58:61], v[210:213], v[218:221], v[58:61]
	v_mfma_f32_16x16x32_bf16 v[54:57], v[202:205], v[226:229], v[54:57]
	v_mfma_f32_16x16x32_bf16 v[50:53], v[210:213], v[226:229], v[50:53]
	v_mfma_f32_16x16x32_bf16 v[46:49], v[202:205], v[234:237], v[46:49]
	v_mfma_f32_16x16x32_bf16 v[42:45], v[210:213], v[234:237], v[42:45]
	v_mfma_f32_16x16x32_bf16 v[38:41], v[202:205], v[242:245], v[38:41]
	v_mfma_f32_16x16x32_bf16 v[34:37], v[210:213], v[242:245], v[34:37]
	s_setprio 0
	s_barrier
	s_add_i32 s3, s3, s26
	v_lshl_add_u64 v[144:145], v[144:145], 0, s[70:71]
	s_mov_b32 m0, s3
	ds_read_b128 v[214:217], v172 offset:49152
	ds_read_b128 v[218:221], v172 offset:50176
	ds_read_b128 v[222:225], v172 offset:51200
	ds_read_b128 v[226:229], v172 offset:52224
	ds_read_b128 v[230:233], v172 offset:53248
	ds_read_b128 v[234:237], v172 offset:54272
	ds_read_b128 v[238:241], v172 offset:55296
	ds_read_b128 v[242:245], v172 offset:56320
	global_load_lds_dwordx4 v[144:145], off
	s_add_i32 m0, s3, 0x2000
	s_add_u32 s0, s0, 0x40080
	v_lshl_add_u64 v[144:145], v[246:247], 0, s[70:71]
	s_addc_u32 s1, s1, 0
	s_add_i32 s3, s6, s26
	global_load_lds_dwordx4 v[144:145], off
	v_lshl_add_u64 v[144:145], s[0:1], 0, v[4:5]
	s_mov_b32 m0, s3
	s_nop 0
	global_load_lds_dwordx4 v[144:145], off
	v_lshl_add_u64 v[144:145], s[0:1], 0, v[134:135]
	s_add_i32 m0, s3, 0x2000
	s_nop 0
	global_load_lds_dwordx4 v[144:145], off
	v_lshl_add_u64 v[144:145], v[248:249], 0, s[70:71]
	s_mov_b32 m0, s35
	s_nop 0
	global_load_lds_dwordx4 v[144:145], off
	v_lshl_add_u64 v[144:145], v[250:251], 0, s[70:71]
	s_mov_b32 m0, s36
	s_nop 0
	global_load_lds_dwordx4 v[144:145], off
	s_waitcnt vmcnt(8)
	s_waitcnt lgkmcnt(0)
	s_barrier
	s_setprio 1
	s_waitcnt lgkmcnt(0)
	v_mfma_f32_16x16x32_bf16 v[94:97], v[140:143], v[214:217], v[94:97]
	v_mfma_f32_16x16x32_bf16 v[90:93], v[190:193], v[214:217], v[90:93]
	v_mfma_f32_16x16x32_bf16 v[86:89], v[140:143], v[222:225], v[86:89]
	v_mfma_f32_16x16x32_bf16 v[82:85], v[190:193], v[222:225], v[82:85]
	v_mfma_f32_16x16x32_bf16 v[78:81], v[140:143], v[230:233], v[78:81]
	v_mfma_f32_16x16x32_bf16 v[74:77], v[190:193], v[230:233], v[74:77]
	v_mfma_f32_16x16x32_bf16 v[70:73], v[140:143], v[238:241], v[70:73]
	v_mfma_f32_16x16x32_bf16 v[66:69], v[190:193], v[238:241], v[66:69]
	v_mfma_f32_16x16x32_bf16 v[94:97], v[174:177], v[218:221], v[94:97]
	v_mfma_f32_16x16x32_bf16 v[90:93], v[194:197], v[218:221], v[90:93]
	v_mfma_f32_16x16x32_bf16 v[86:89], v[174:177], v[226:229], v[86:89]
	v_mfma_f32_16x16x32_bf16 v[82:85], v[194:197], v[226:229], v[82:85]
	v_mfma_f32_16x16x32_bf16 v[78:81], v[174:177], v[234:237], v[78:81]
	v_mfma_f32_16x16x32_bf16 v[74:77], v[194:197], v[234:237], v[74:77]
	v_mfma_f32_16x16x32_bf16 v[70:73], v[174:177], v[242:245], v[70:73]
	v_mfma_f32_16x16x32_bf16 v[66:69], v[194:197], v[242:245], v[66:69]
	s_setprio 0
	s_setprio 1
	v_mfma_f32_16x16x32_bf16 v[30:33], v[198:201], v[214:217], v[30:33]
	v_mfma_f32_16x16x32_bf16 v[26:29], v[206:209], v[214:217], v[26:29]
	v_mfma_f32_16x16x32_bf16 v[22:25], v[198:201], v[222:225], v[22:25]
	v_mfma_f32_16x16x32_bf16 v[18:21], v[206:209], v[222:225], v[18:21]
	v_mfma_f32_16x16x32_bf16 v[14:17], v[198:201], v[230:233], v[14:17]
	v_mfma_f32_16x16x32_bf16 v[10:13], v[206:209], v[230:233], v[10:13]
	v_mfma_f32_16x16x32_bf16 v[6:9], v[198:201], v[238:241], v[6:9]
	v_mfma_f32_16x16x32_bf16 v[0:3], v[206:209], v[238:241], v[0:3]
	v_mfma_f32_16x16x32_bf16 v[30:33], v[202:205], v[218:221], v[30:33]
	v_mfma_f32_16x16x32_bf16 v[26:29], v[210:213], v[218:221], v[26:29]
	v_mfma_f32_16x16x32_bf16 v[22:25], v[202:205], v[226:229], v[22:25]
	v_mfma_f32_16x16x32_bf16 v[18:21], v[210:213], v[226:229], v[18:21]
	v_mfma_f32_16x16x32_bf16 v[14:17], v[202:205], v[234:237], v[14:17]
	v_mfma_f32_16x16x32_bf16 v[10:13], v[210:213], v[234:237], v[10:13]
	v_mfma_f32_16x16x32_bf16 v[6:9], v[202:205], v[242:245], v[6:9]
	v_mfma_f32_16x16x32_bf16 v[0:3], v[210:213], v[242:245], v[0:3]
	s_setprio 0
	s_barrier
	s_add_i32 s24, s24, 2
	s_add_u32 s22, s22, 0x100
	s_addc_u32 s23, s23, 0
	s_add_u32 s9, s9, 0x100
	s_addc_u32 s10, s10, 0
	s_cmp_gt_u32 s24, 13
	s_cbranch_scc0 .LBB0_205
	s_and_b64 vcc, exec, s[46:47]
	s_cbranch_vccz .LBB0_208
	s_barrier

.LBB0_227:
	s_ashr_i32 s47, s46, 31
	s_lshl_b64 s[2:3], s[46:47], 19
	v_readlane_b32 s4, v253, 25
	v_readlane_b32 s5, v253, 26
	s_add_u32 s82, s4, s2
	s_addc_u32 s83, s5, s3
	s_and_b64 s[2:3], s[40:41], exec
	s_cselect_b32 s2, s83, s15
	s_cselect_b32 s8, s82, s14
	s_add_u32 s22, s0, 0x40080
	s_addc_u32 s23, s1, 0
	s_add_u32 s9, s14, 0x100
	v_mov_b32_e32 v0, 0
	s_addc_u32 s10, s15, 0
	s_mov_b32 s24, -2
	v_mov_b32_e32 v1, v0
	v_mov_b32_e32 v2, v0
	v_mov_b32_e32 v3, v0
	v_mov_b32_e32 v6, v0
	v_mov_b32_e32 v7, v0
	v_mov_b32_e32 v8, v0
	v_mov_b32_e32 v9, v0
	v_mov_b32_e32 v10, v0
	v_mov_b32_e32 v11, v0
	v_mov_b32_e32 v12, v0
	v_mov_b32_e32 v13, v0
	v_mov_b32_e32 v14, v0
	v_mov_b32_e32 v15, v0
	v_mov_b32_e32 v16, v0
	v_mov_b32_e32 v17, v0
	v_mov_b32_e32 v18, v0
	v_mov_b32_e32 v19, v0
	v_mov_b32_e32 v20, v0
	v_mov_b32_e32 v21, v0
	v_mov_b32_e32 v22, v0
	v_mov_b32_e32 v23, v0
	v_mov_b32_e32 v24, v0
	v_mov_b32_e32 v25, v0
	v_mov_b32_e32 v26, v0
	v_mov_b32_e32 v27, v0
	v_mov_b32_e32 v28, v0
	v_mov_b32_e32 v29, v0
	v_mov_b32_e32 v30, v0
	v_mov_b32_e32 v31, v0
	v_mov_b32_e32 v32, v0
	v_mov_b32_e32 v33, v0
	v_mov_b32_e32 v62, v0
	v_mov_b32_e32 v63, v0
	v_mov_b32_e32 v64, v0
	v_mov_b32_e32 v65, v0
	v_mov_b32_e32 v70, v0
	v_mov_b32_e32 v71, v0
	v_mov_b32_e32 v72, v0
	v_mov_b32_e32 v73, v0
	v_mov_b32_e32 v74, v0
	v_mov_b32_e32 v75, v0
	v_mov_b32_e32 v76, v0
	v_mov_b32_e32 v77, v0
	v_mov_b32_e32 v78, v0
	v_mov_b32_e32 v79, v0
	v_mov_b32_e32 v80, v0
	v_mov_b32_e32 v81, v0
	v_mov_b32_e32 v82, v0
	v_mov_b32_e32 v83, v0
	v_mov_b32_e32 v84, v0
	v_mov_b32_e32 v85, v0
	v_mov_b32_e32 v86, v0
	v_mov_b32_e32 v87, v0
	v_mov_b32_e32 v88, v0
	v_mov_b32_e32 v89, v0
	v_mov_b32_e32 v90, v0
	v_mov_b32_e32 v91, v0
	v_mov_b32_e32 v92, v0
	v_mov_b32_e32 v93, v0
	v_mov_b32_e32 v94, v0
	v_mov_b32_e32 v95, v0
	v_mov_b32_e32 v96, v0
	v_mov_b32_e32 v97, v0
	v_mov_b32_e32 v34, v0
	v_mov_b32_e32 v35, v0
	v_mov_b32_e32 v36, v0
	v_mov_b32_e32 v37, v0
	v_mov_b32_e32 v38, v0
	v_mov_b32_e32 v39, v0
	v_mov_b32_e32 v40, v0
	v_mov_b32_e32 v41, v0
	v_mov_b32_e32 v42, v0
	v_mov_b32_e32 v43, v0
	v_mov_b32_e32 v44, v0
	v_mov_b32_e32 v45, v0
	v_mov_b32_e32 v46, v0
	v_mov_b32_e32 v47, v0
	v_mov_b32_e32 v48, v0
	v_mov_b32_e32 v49, v0
	v_mov_b32_e32 v50, v0
	v_mov_b32_e32 v51, v0
	v_mov_b32_e32 v52, v0
	v_mov_b32_e32 v53, v0
	v_mov_b32_e32 v54, v0
	v_mov_b32_e32 v55, v0
	v_mov_b32_e32 v56, v0
	v_mov_b32_e32 v57, v0
	v_mov_b32_e32 v58, v0
	v_mov_b32_e32 v59, v0
	v_mov_b32_e32 v60, v0
	v_mov_b32_e32 v61, v0
	v_mov_b32_e32 v66, v0
	v_mov_b32_e32 v67, v0
	v_mov_b32_e32 v68, v0
	v_mov_b32_e32 v69, v0
	v_mov_b32_e32 v98, v0
	v_mov_b32_e32 v99, v0
	v_mov_b32_e32 v100, v0
	v_mov_b32_e32 v101, v0
	v_mov_b32_e32 v102, v0
	v_mov_b32_e32 v103, v0
	v_mov_b32_e32 v104, v0
	v_mov_b32_e32 v105, v0
	v_mov_b32_e32 v106, v0
	v_mov_b32_e32 v107, v0
	v_mov_b32_e32 v108, v0
	v_mov_b32_e32 v109, v0
	v_mov_b32_e32 v110, v0
	v_mov_b32_e32 v111, v0
	v_mov_b32_e32 v112, v0
	v_mov_b32_e32 v113, v0
	v_mov_b32_e32 v114, v0
	v_mov_b32_e32 v115, v0
	v_mov_b32_e32 v116, v0
	v_mov_b32_e32 v117, v0
	v_mov_b32_e32 v118, v0
	v_mov_b32_e32 v119, v0
	v_mov_b32_e32 v120, v0
	v_mov_b32_e32 v121, v0
	v_mov_b32_e32 v122, v0
	v_mov_b32_e32 v123, v0
	v_mov_b32_e32 v124, v0
	v_mov_b32_e32 v125, v0
	v_mov_b32_e32 v126, v0
	v_mov_b32_e32 v127, v0
	v_mov_b32_e32 v128, v0
	v_mov_b32_e32 v129, v0
	s_cmp_eq_u32 s37, 1
	s_cbranch_scc1 .LBB0_228
	s_add_u32 s0, s22, 0xfffc0080
	s_addc_u32 s1, s23, -1
	s_add_i32 s3, 0, 0x10000
	s_cmp_eq_u32 s24, 12
	s_cselect_b32 s15, s49, s1
	s_cselect_b32 s14, s48, s0
	v_add_u32_e32 v162, s3, v149
	s_cselect_b32 s1, s2, s10
	s_cselect_b32 s0, s8, s9
	s_add_i32 s6, 0, 0x14000
	ds_read_b128 v[140:143], v162
	ds_read_b128 v[144:147], v162 offset:1024
	ds_read_b128 v[172:175], v162 offset:2048
	ds_read_b128 v[190:193], v162 offset:3072
	v_add_u32_e32 v162, s6, v149
	ds_read_b128 v[194:197], v162
	ds_read_b128 v[198:201], v162 offset:1024
	ds_read_b128 v[202:205], v162 offset:2048
	ds_read_b128 v[206:209], v162 offset:3072
	v_lshl_add_u64 v[162:163], s[22:23], 0, v[136:137]
	s_add_i32 m0, s27, 0xc000
	ds_read_b128 v[210:213], v151
	ds_read_b128 v[214:217], v151 offset:1024
	ds_read_b128 v[218:221], v151 offset:2048
	ds_read_b128 v[222:225], v151 offset:3072
	ds_read_b128 v[226:229], v151 offset:4096
	ds_read_b128 v[230:233], v151 offset:5120
	ds_read_b128 v[234:237], v151 offset:6144
	ds_read_b128 v[238:241], v151 offset:7168
	global_load_lds_dwordx4 v[162:163], off
	v_lshl_add_u64 v[162:163], s[22:23], 0, v[138:139]
	s_add_i32 m0, s27, 0xe000
	s_nop 0
	global_load_lds_dwordx4 v[162:163], off
	s_waitcnt vmcnt(24)
	s_waitcnt lgkmcnt(0)
	s_barrier
	s_setprio 1
	s_waitcnt lgkmcnt(0)
	v_mfma_f32_16x16x32_bf16 v[126:129], v[140:143], v[210:213], v[126:129]
	v_mfma_f32_16x16x32_bf16 v[122:125], v[172:175], v[210:213], v[122:125]
	v_mfma_f32_16x16x32_bf16 v[118:121], v[140:143], v[218:221], v[118:121]
	v_mfma_f32_16x16x32_bf16 v[114:117], v[172:175], v[218:221], v[114:117]
	v_mfma_f32_16x16x32_bf16 v[110:113], v[140:143], v[226:229], v[110:113]
	v_mfma_f32_16x16x32_bf16 v[106:109], v[172:175], v[226:229], v[106:109]
	v_mfma_f32_16x16x32_bf16 v[102:105], v[140:143], v[234:237], v[102:105]
	v_mfma_f32_16x16x32_bf16 v[98:101], v[172:175], v[234:237], v[98:101]
	v_mfma_f32_16x16x32_bf16 v[126:129], v[144:147], v[214:217], v[126:129]
	v_mfma_f32_16x16x32_bf16 v[122:125], v[190:193], v[214:217], v[122:125]
	v_mfma_f32_16x16x32_bf16 v[118:121], v[144:147], v[222:225], v[118:121]
	v_mfma_f32_16x16x32_bf16 v[114:117], v[190:193], v[222:225], v[114:117]
	v_mfma_f32_16x16x32_bf16 v[110:113], v[144:147], v[230:233], v[110:113]
	v_mfma_f32_16x16x32_bf16 v[106:109], v[190:193], v[230:233], v[106:109]
	v_mfma_f32_16x16x32_bf16 v[102:105], v[144:147], v[238:241], v[102:105]
	v_mfma_f32_16x16x32_bf16 v[98:101], v[190:193], v[238:241], v[98:101]
	s_setprio 0
	s_setprio 1
	v_mfma_f32_16x16x32_bf16 v[66:69], v[194:197], v[210:213], v[66:69]
	v_mfma_f32_16x16x32_bf16 v[58:61], v[202:205], v[210:213], v[58:61]
	v_mfma_f32_16x16x32_bf16 v[54:57], v[194:197], v[218:221], v[54:57]
	v_mfma_f32_16x16x32_bf16 v[50:53], v[202:205], v[218:221], v[50:53]
	v_mfma_f32_16x16x32_bf16 v[46:49], v[194:197], v[226:229], v[46:49]
	v_mfma_f32_16x16x32_bf16 v[42:45], v[202:205], v[226:229], v[42:45]
	v_mfma_f32_16x16x32_bf16 v[38:41], v[194:197], v[234:237], v[38:41]
	v_mfma_f32_16x16x32_bf16 v[34:37], v[202:205], v[234:237], v[34:37]
	v_mfma_f32_16x16x32_bf16 v[66:69], v[198:201], v[214:217], v[66:69]
	v_mfma_f32_16x16x32_bf16 v[58:61], v[206:209], v[214:217], v[58:61]
	v_mfma_f32_16x16x32_bf16 v[54:57], v[198:201], v[222:225], v[54:57]
	v_mfma_f32_16x16x32_bf16 v[50:53], v[206:209], v[222:225], v[50:53]
	v_mfma_f32_16x16x32_bf16 v[46:49], v[198:201], v[230:233], v[46:49]
	v_mfma_f32_16x16x32_bf16 v[42:45], v[206:209], v[230:233], v[42:45]
	v_mfma_f32_16x16x32_bf16 v[38:41], v[198:201], v[238:241], v[38:41]
	v_mfma_f32_16x16x32_bf16 v[34:37], v[206:209], v[238:241], v[34:37]
	s_setprio 0
	s_barrier
	s_add_i32 s3, s3, s26
	v_lshl_add_u64 v[162:163], s[0:1], 0, v[4:5]
	s_mov_b32 m0, s3
	ds_read_b128 v[210:213], v151 offset:16384
	ds_read_b128 v[214:217], v151 offset:17408
	ds_read_b128 v[218:221], v151 offset:18432
	ds_read_b128 v[222:225], v151 offset:19456
	ds_read_b128 v[226:229], v151 offset:20480
	ds_read_b128 v[230:233], v151 offset:21504
	ds_read_b128 v[234:237], v151 offset:22528
	ds_read_b128 v[238:241], v151 offset:23552
	global_load_lds_dwordx4 v[162:163], off
	s_add_i32 m0, s3, 0x2000
	s_add_u32 s4, s0, 0x40000
	v_lshl_add_u64 v[166:167], s[0:1], 0, v[134:135]
	s_addc_u32 s5, s1, 0
	s_add_i32 s3, s6, s26
	global_load_lds_dwordx4 v[166:167], off
	v_lshl_add_u64 v[176:177], s[4:5], 0, v[4:5]
	s_mov_b32 m0, s3
	v_lshl_add_u64 v[180:181], s[14:15], 0, v[132:133]
	global_load_lds_dwordx4 v[176:177], off
	v_lshl_add_u64 v[176:177], s[4:5], 0, v[134:135]
	s_add_i32 m0, s3, 0x2000
	s_nop 0
	global_load_lds_dwordx4 v[176:177], off
	v_lshl_add_u64 v[176:177], s[14:15], 0, v[130:131]
	s_mov_b32 m0, s27
	s_nop 0
	global_load_lds_dwordx4 v[176:177], off
	s_mov_b32 m0, s30
	s_nop 0
	global_load_lds_dwordx4 v[180:181], off
	s_waitcnt vmcnt(24)
	s_waitcnt lgkmcnt(0)
	s_barrier
	s_setprio 1
	s_waitcnt lgkmcnt(0)
	v_mfma_f32_16x16x32_bf16 v[94:97], v[140:143], v[210:213], v[94:97]
	v_mfma_f32_16x16x32_bf16 v[90:93], v[172:175], v[210:213], v[90:93]
	v_mfma_f32_16x16x32_bf16 v[86:89], v[140:143], v[218:221], v[86:89]
	v_mfma_f32_16x16x32_bf16 v[82:85], v[172:175], v[218:221], v[82:85]
	v_mfma_f32_16x16x32_bf16 v[78:81], v[140:143], v[226:229], v[78:81]
	v_mfma_f32_16x16x32_bf16 v[74:77], v[172:175], v[226:229], v[74:77]
	v_mfma_f32_16x16x32_bf16 v[70:73], v[140:143], v[234:237], v[70:73]
	v_mfma_f32_16x16x32_bf16 v[62:65], v[172:175], v[234:237], v[62:65]
	v_mfma_f32_16x16x32_bf16 v[94:97], v[144:147], v[214:217], v[94:97]
	v_mfma_f32_16x16x32_bf16 v[90:93], v[190:193], v[214:217], v[90:93]
	v_mfma_f32_16x16x32_bf16 v[86:89], v[144:147], v[222:225], v[86:89]
	v_mfma_f32_16x16x32_bf16 v[82:85], v[190:193], v[222:225], v[82:85]
	v_mfma_f32_16x16x32_bf16 v[78:81], v[144:147], v[230:233], v[78:81]
	v_mfma_f32_16x16x32_bf16 v[74:77], v[190:193], v[230:233], v[74:77]
	v_mfma_f32_16x16x32_bf16 v[70:73], v[144:147], v[238:241], v[70:73]
	v_mfma_f32_16x16x32_bf16 v[62:65], v[190:193], v[238:241], v[62:65]
	s_setprio 0
	s_setprio 1
	v_mfma_f32_16x16x32_bf16 v[30:33], v[194:197], v[210:213], v[30:33]
	v_mfma_f32_16x16x32_bf16 v[26:29], v[202:205], v[210:213], v[26:29]
	v_mfma_f32_16x16x32_bf16 v[22:25], v[194:197], v[218:221], v[22:25]
	v_mfma_f32_16x16x32_bf16 v[18:21], v[202:205], v[218:221], v[18:21]
	v_mfma_f32_16x16x32_bf16 v[14:17], v[194:197], v[226:229], v[14:17]
	v_mfma_f32_16x16x32_bf16 v[10:13], v[202:205], v[226:229], v[10:13]
	v_mfma_f32_16x16x32_bf16 v[6:9], v[194:197], v[234:237], v[6:9]
	v_mfma_f32_16x16x32_bf16 v[0:3], v[202:205], v[234:237], v[0:3]
	v_mfma_f32_16x16x32_bf16 v[30:33], v[198:201], v[214:217], v[30:33]
	v_mfma_f32_16x16x32_bf16 v[26:29], v[206:209], v[214:217], v[26:29]
	v_mfma_f32_16x16x32_bf16 v[22:25], v[198:201], v[222:225], v[22:25]
	v_mfma_f32_16x16x32_bf16 v[18:21], v[206:209], v[222:225], v[18:21]
	v_mfma_f32_16x16x32_bf16 v[14:17], v[198:201], v[230:233], v[14:17]
	v_mfma_f32_16x16x32_bf16 v[10:13], v[206:209], v[230:233], v[10:13]
	v_mfma_f32_16x16x32_bf16 v[6:9], v[198:201], v[238:241], v[6:9]
	v_mfma_f32_16x16x32_bf16 v[0:3], v[206:209], v[238:241], v[0:3]
	s_setprio 0
	s_barrier
	s_branch .Lpeelmid_228

.Lpeelmid_228:
	s_add_i32 s3, 0, 0x18000
	v_add_u32_e32 v164, s3, v149
	s_add_i32 s6, 0, 0x1c000
	ds_read_b128 v[140:143], v164
	ds_read_b128 v[144:147], v164 offset:1024
	ds_read_b128 v[172:175], v164 offset:2048
	ds_read_b128 v[190:193], v164 offset:3072
	v_add_u32_e32 v164, s6, v149
	ds_read_b128 v[194:197], v164
	ds_read_b128 v[198:201], v164 offset:1024
	ds_read_b128 v[202:205], v164 offset:2048
	ds_read_b128 v[206:209], v164 offset:3072
	s_add_u32 s4, s14, 0x40000
	s_addc_u32 s5, s15, 0
	s_mov_b32 m0, s31
	v_lshl_add_u64 v[242:243], s[4:5], 0, v[130:131]
	ds_read_b128 v[210:213], v151 offset:32768
	ds_read_b128 v[214:217], v151 offset:33792
	ds_read_b128 v[218:221], v151 offset:34816
	ds_read_b128 v[222:225], v151 offset:35840
	ds_read_b128 v[226:229], v151 offset:36864
	ds_read_b128 v[230:233], v151 offset:37888
	ds_read_b128 v[234:237], v151 offset:38912
	ds_read_b128 v[238:241], v151 offset:39936
	global_load_lds_dwordx4 v[242:243], off
	v_lshl_add_u64 v[242:243], s[4:5], 0, v[132:133]
	s_mov_b32 m0, s34
	s_nop 0
	global_load_lds_dwordx4 v[242:243], off
	s_waitcnt vmcnt(8)
	s_waitcnt lgkmcnt(0)
	s_barrier
	s_setprio 1
	s_waitcnt lgkmcnt(0)
	v_mfma_f32_16x16x32_bf16 v[126:129], v[140:143], v[210:213], v[126:129]
	v_mfma_f32_16x16x32_bf16 v[122:125], v[172:175], v[210:213], v[122:125]
	v_mfma_f32_16x16x32_bf16 v[118:121], v[140:143], v[218:221], v[118:121]
	v_mfma_f32_16x16x32_bf16 v[114:117], v[172:175], v[218:221], v[114:117]
	v_mfma_f32_16x16x32_bf16 v[110:113], v[140:143], v[226:229], v[110:113]
	v_mfma_f32_16x16x32_bf16 v[106:109], v[172:175], v[226:229], v[106:109]
	v_mfma_f32_16x16x32_bf16 v[102:105], v[140:143], v[234:237], v[102:105]
	v_mfma_f32_16x16x32_bf16 v[98:101], v[172:175], v[234:237], v[98:101]
	v_mfma_f32_16x16x32_bf16 v[126:129], v[144:147], v[214:217], v[126:129]
	v_mfma_f32_16x16x32_bf16 v[122:125], v[190:193], v[214:217], v[122:125]
	v_mfma_f32_16x16x32_bf16 v[118:121], v[144:147], v[222:225], v[118:121]
	v_mfma_f32_16x16x32_bf16 v[114:117], v[190:193], v[222:225], v[114:117]
	v_mfma_f32_16x16x32_bf16 v[110:113], v[144:147], v[230:233], v[110:113]
	v_mfma_f32_16x16x32_bf16 v[106:109], v[190:193], v[230:233], v[106:109]
	v_mfma_f32_16x16x32_bf16 v[102:105], v[144:147], v[238:241], v[102:105]
	v_mfma_f32_16x16x32_bf16 v[98:101], v[190:193], v[238:241], v[98:101]
	s_setprio 0
	s_setprio 1
	v_mfma_f32_16x16x32_bf16 v[66:69], v[194:197], v[210:213], v[66:69]
	v_mfma_f32_16x16x32_bf16 v[58:61], v[202:205], v[210:213], v[58:61]
	v_mfma_f32_16x16x32_bf16 v[54:57], v[194:197], v[218:221], v[54:57]
	v_mfma_f32_16x16x32_bf16 v[50:53], v[202:205], v[218:221], v[50:53]
	v_mfma_f32_16x16x32_bf16 v[46:49], v[194:197], v[226:229], v[46:49]
	v_mfma_f32_16x16x32_bf16 v[42:45], v[202:205], v[226:229], v[42:45]
	v_mfma_f32_16x16x32_bf16 v[38:41], v[194:197], v[234:237], v[38:41]
	v_mfma_f32_16x16x32_bf16 v[34:37], v[202:205], v[234:237], v[34:37]
	v_mfma_f32_16x16x32_bf16 v[66:69], v[198:201], v[214:217], v[66:69]
	v_mfma_f32_16x16x32_bf16 v[58:61], v[206:209], v[214:217], v[58:61]
	v_mfma_f32_16x16x32_bf16 v[54:57], v[198:201], v[222:225], v[54:57]
	v_mfma_f32_16x16x32_bf16 v[50:53], v[206:209], v[222:225], v[50:53]
	v_mfma_f32_16x16x32_bf16 v[46:49], v[198:201], v[230:233], v[46:49]
	v_mfma_f32_16x16x32_bf16 v[42:45], v[206:209], v[230:233], v[42:45]
	v_mfma_f32_16x16x32_bf16 v[38:41], v[198:201], v[238:241], v[38:41]
	v_mfma_f32_16x16x32_bf16 v[34:37], v[206:209], v[238:241], v[34:37]
	s_setprio 0
	s_barrier
	s_add_i32 s3, s3, s26
	v_lshl_add_u64 v[162:163], v[162:163], 0, s[70:71]
	s_mov_b32 m0, s3
	ds_read_b128 v[210:213], v151 offset:49152
	ds_read_b128 v[214:217], v151 offset:50176
	ds_read_b128 v[218:221], v151 offset:51200
	ds_read_b128 v[222:225], v151 offset:52224
	ds_read_b128 v[226:229], v151 offset:53248
	ds_read_b128 v[230:233], v151 offset:54272
	ds_read_b128 v[234:237], v151 offset:55296
	ds_read_b128 v[238:241], v151 offset:56320
	global_load_lds_dwordx4 v[162:163], off
	s_add_i32 m0, s3, 0x2000
	s_add_u32 s0, s0, 0x40080
	v_lshl_add_u64 v[162:163], v[166:167], 0, s[70:71]
	s_addc_u32 s1, s1, 0
	s_add_i32 s3, s6, s26
	global_load_lds_dwordx4 v[162:163], off
	v_lshl_add_u64 v[162:163], s[0:1], 0, v[4:5]
	s_mov_b32 m0, s3
	s_nop 0
	global_load_lds_dwordx4 v[162:163], off
	v_lshl_add_u64 v[162:163], s[0:1], 0, v[134:135]
	s_add_i32 m0, s3, 0x2000
	s_nop 0
	global_load_lds_dwordx4 v[162:163], off
	v_lshl_add_u64 v[162:163], v[176:177], 0, s[70:71]
	s_mov_b32 m0, s35
	s_nop 0
	global_load_lds_dwordx4 v[162:163], off
	v_lshl_add_u64 v[162:163], v[180:181], 0, s[70:71]
	s_mov_b32 m0, s36
	s_nop 0
	global_load_lds_dwordx4 v[162:163], off
	s_waitcnt vmcnt(8)
	s_waitcnt lgkmcnt(0)
	s_barrier
	s_setprio 1
	s_waitcnt lgkmcnt(0)
	v_mfma_f32_16x16x32_bf16 v[94:97], v[140:143], v[210:213], v[94:97]
	v_mfma_f32_16x16x32_bf16 v[90:93], v[172:175], v[210:213], v[90:93]
	v_mfma_f32_16x16x32_bf16 v[86:89], v[140:143], v[218:221], v[86:89]
	v_mfma_f32_16x16x32_bf16 v[82:85], v[172:175], v[218:221], v[82:85]
	v_mfma_f32_16x16x32_bf16 v[78:81], v[140:143], v[226:229], v[78:81]
	v_mfma_f32_16x16x32_bf16 v[74:77], v[172:175], v[226:229], v[74:77]
	v_mfma_f32_16x16x32_bf16 v[70:73], v[140:143], v[234:237], v[70:73]
	v_mfma_f32_16x16x32_bf16 v[62:65], v[172:175], v[234:237], v[62:65]
	v_mfma_f32_16x16x32_bf16 v[94:97], v[144:147], v[214:217], v[94:97]
	v_mfma_f32_16x16x32_bf16 v[90:93], v[190:193], v[214:217], v[90:93]
	v_mfma_f32_16x16x32_bf16 v[86:89], v[144:147], v[222:225], v[86:89]
	v_mfma_f32_16x16x32_bf16 v[82:85], v[190:193], v[222:225], v[82:85]
	v_mfma_f32_16x16x32_bf16 v[78:81], v[144:147], v[230:233], v[78:81]
	v_mfma_f32_16x16x32_bf16 v[74:77], v[190:193], v[230:233], v[74:77]
	v_mfma_f32_16x16x32_bf16 v[70:73], v[144:147], v[238:241], v[70:73]
	v_mfma_f32_16x16x32_bf16 v[62:65], v[190:193], v[238:241], v[62:65]
	s_setprio 0
	s_setprio 1
	v_mfma_f32_16x16x32_bf16 v[30:33], v[194:197], v[210:213], v[30:33]
	v_mfma_f32_16x16x32_bf16 v[26:29], v[202:205], v[210:213], v[26:29]
	v_mfma_f32_16x16x32_bf16 v[22:25], v[194:197], v[218:221], v[22:25]
	v_mfma_f32_16x16x32_bf16 v[18:21], v[202:205], v[218:221], v[18:21]
	v_mfma_f32_16x16x32_bf16 v[14:17], v[194:197], v[226:229], v[14:17]
	v_mfma_f32_16x16x32_bf16 v[10:13], v[202:205], v[226:229], v[10:13]
	v_mfma_f32_16x16x32_bf16 v[6:9], v[194:197], v[234:237], v[6:9]
	v_mfma_f32_16x16x32_bf16 v[0:3], v[202:205], v[234:237], v[0:3]
	v_mfma_f32_16x16x32_bf16 v[30:33], v[198:201], v[214:217], v[30:33]
	v_mfma_f32_16x16x32_bf16 v[26:29], v[206:209], v[214:217], v[26:29]
	v_mfma_f32_16x16x32_bf16 v[22:25], v[198:201], v[222:225], v[22:25]
	v_mfma_f32_16x16x32_bf16 v[18:21], v[206:209], v[222:225], v[18:21]
	v_mfma_f32_16x16x32_bf16 v[14:17], v[198:201], v[230:233], v[14:17]
	v_mfma_f32_16x16x32_bf16 v[10:13], v[206:209], v[230:233], v[10:13]
	v_mfma_f32_16x16x32_bf16 v[6:9], v[198:201], v[238:241], v[6:9]
	v_mfma_f32_16x16x32_bf16 v[0:3], v[206:209], v[238:241], v[0:3]
	s_setprio 0
	s_barrier
	s_add_i32 s24, s24, 2
	s_add_u32 s22, s22, 0x100
	s_addc_u32 s23, s23, 0
	s_add_u32 s9, s9, 0x100
	s_addc_u32 s10, s10, 0
	s_cmp_gt_u32 s24, 13
	s_cbranch_scc0 .LBB0_228
	s_and_b64 vcc, exec, s[44:45]
	s_cbranch_vccz .LBB0_231
	s_barrier

.LBB0_251:
	s_ashr_i32 s47, s46, 31
	s_lshl_b64 s[2:3], s[46:47], 20
	v_readlane_b32 s4, v253, 36
	s_add_u32 s82, s4, s2
	v_readlane_b32 s2, v253, 37
	s_addc_u32 s83, s2, s3
	s_and_b64 s[2:3], s[40:41], exec
	s_cselect_b32 s2, s83, s15
	s_cselect_b32 s8, s82, s14
	s_add_u32 s22, s0, 0x80080
	s_addc_u32 s23, s1, 0
	s_add_u32 s9, s14, 0x100
	v_mov_b32_e32 v0, 0
	s_addc_u32 s10, s15, 0
	s_mov_b32 s24, -2
	v_mov_b32_e32 v1, v0
	v_mov_b32_e32 v2, v0
	v_mov_b32_e32 v3, v0
	v_mov_b32_e32 v6, v0
	v_mov_b32_e32 v7, v0
	v_mov_b32_e32 v8, v0
	v_mov_b32_e32 v9, v0
	v_mov_b32_e32 v10, v0
	v_mov_b32_e32 v11, v0
	v_mov_b32_e32 v12, v0
	v_mov_b32_e32 v13, v0
	v_mov_b32_e32 v14, v0
	v_mov_b32_e32 v15, v0
	v_mov_b32_e32 v16, v0
	v_mov_b32_e32 v17, v0
	v_mov_b32_e32 v18, v0
	v_mov_b32_e32 v19, v0
	v_mov_b32_e32 v20, v0
	v_mov_b32_e32 v21, v0
	v_mov_b32_e32 v22, v0
	v_mov_b32_e32 v23, v0
	v_mov_b32_e32 v24, v0
	v_mov_b32_e32 v25, v0
	v_mov_b32_e32 v26, v0
	v_mov_b32_e32 v27, v0
	v_mov_b32_e32 v28, v0
	v_mov_b32_e32 v29, v0
	v_mov_b32_e32 v30, v0
	v_mov_b32_e32 v31, v0
	v_mov_b32_e32 v32, v0
	v_mov_b32_e32 v33, v0
	v_mov_b32_e32 v62, v0
	v_mov_b32_e32 v63, v0
	v_mov_b32_e32 v64, v0
	v_mov_b32_e32 v65, v0
	v_mov_b32_e32 v70, v0
	v_mov_b32_e32 v71, v0
	v_mov_b32_e32 v72, v0
	v_mov_b32_e32 v73, v0
	v_mov_b32_e32 v74, v0
	v_mov_b32_e32 v75, v0
	v_mov_b32_e32 v76, v0
	v_mov_b32_e32 v77, v0
	v_mov_b32_e32 v78, v0
	v_mov_b32_e32 v79, v0
	v_mov_b32_e32 v80, v0
	v_mov_b32_e32 v81, v0
	v_mov_b32_e32 v82, v0
	v_mov_b32_e32 v83, v0
	v_mov_b32_e32 v84, v0
	v_mov_b32_e32 v85, v0
	v_mov_b32_e32 v86, v0
	v_mov_b32_e32 v87, v0
	v_mov_b32_e32 v88, v0
	v_mov_b32_e32 v89, v0
	v_mov_b32_e32 v90, v0
	v_mov_b32_e32 v91, v0
	v_mov_b32_e32 v92, v0
	v_mov_b32_e32 v93, v0
	v_mov_b32_e32 v94, v0
	v_mov_b32_e32 v95, v0
	v_mov_b32_e32 v96, v0
	v_mov_b32_e32 v97, v0
	v_mov_b32_e32 v34, v0
	v_mov_b32_e32 v35, v0
	v_mov_b32_e32 v36, v0
	v_mov_b32_e32 v37, v0
	v_mov_b32_e32 v38, v0
	v_mov_b32_e32 v39, v0
	v_mov_b32_e32 v40, v0
	v_mov_b32_e32 v41, v0
	v_mov_b32_e32 v42, v0
	v_mov_b32_e32 v43, v0
	v_mov_b32_e32 v44, v0
	v_mov_b32_e32 v45, v0
	v_mov_b32_e32 v46, v0
	v_mov_b32_e32 v47, v0
	v_mov_b32_e32 v48, v0
	v_mov_b32_e32 v49, v0
	v_mov_b32_e32 v50, v0
	v_mov_b32_e32 v51, v0
	v_mov_b32_e32 v52, v0
	v_mov_b32_e32 v53, v0
	v_mov_b32_e32 v54, v0
	v_mov_b32_e32 v55, v0
	v_mov_b32_e32 v56, v0
	v_mov_b32_e32 v57, v0
	v_mov_b32_e32 v58, v0
	v_mov_b32_e32 v59, v0
	v_mov_b32_e32 v60, v0
	v_mov_b32_e32 v61, v0
	v_mov_b32_e32 v66, v0
	v_mov_b32_e32 v67, v0
	v_mov_b32_e32 v68, v0
	v_mov_b32_e32 v69, v0
	v_mov_b32_e32 v98, v0
	v_mov_b32_e32 v99, v0
	v_mov_b32_e32 v100, v0
	v_mov_b32_e32 v101, v0
	v_mov_b32_e32 v102, v0
	v_mov_b32_e32 v103, v0
	v_mov_b32_e32 v104, v0
	v_mov_b32_e32 v105, v0
	v_mov_b32_e32 v106, v0
	v_mov_b32_e32 v107, v0
	v_mov_b32_e32 v108, v0
	v_mov_b32_e32 v109, v0
	v_mov_b32_e32 v110, v0
	v_mov_b32_e32 v111, v0
	v_mov_b32_e32 v112, v0
	v_mov_b32_e32 v113, v0
	v_mov_b32_e32 v114, v0
	v_mov_b32_e32 v115, v0
	v_mov_b32_e32 v116, v0
	v_mov_b32_e32 v117, v0
	v_mov_b32_e32 v118, v0
	v_mov_b32_e32 v119, v0
	v_mov_b32_e32 v120, v0
	v_mov_b32_e32 v121, v0
	v_mov_b32_e32 v122, v0
	v_mov_b32_e32 v123, v0
	v_mov_b32_e32 v124, v0
	v_mov_b32_e32 v125, v0
	v_mov_b32_e32 v126, v0
	v_mov_b32_e32 v127, v0
	v_mov_b32_e32 v128, v0
	v_mov_b32_e32 v129, v0
	s_cmp_eq_u32 s37, 1
	s_cbranch_scc1 .LBB0_252
	s_add_u32 s0, s22, 0xfff80080
	s_addc_u32 s1, s23, -1
	s_add_i32 s3, 0, 0x10000
	s_cmp_eq_u32 s24, 28
	s_cselect_b32 s15, s49, s1
	s_cselect_b32 s14, s48, s0
	v_add_u32_e32 v162, s3, v141
	s_cselect_b32 s1, s2, s10
	s_cselect_b32 s0, s8, s9
	s_add_i32 s6, 0, 0x14000
	ds_read_b128 v[144:147], v162
	ds_read_b128 v[148:151], v162 offset:1024
	ds_read_b128 v[172:175], v162 offset:2048
	ds_read_b128 v[190:193], v162 offset:3072
	v_add_u32_e32 v162, s6, v141
	ds_read_b128 v[194:197], v162
	ds_read_b128 v[198:201], v162 offset:1024
	ds_read_b128 v[202:205], v162 offset:2048
	ds_read_b128 v[206:209], v162 offset:3072
	v_lshl_add_u64 v[162:163], s[22:23], 0, v[136:137]
	s_add_i32 m0, s27, 0xc000
	ds_read_b128 v[210:213], v143
	ds_read_b128 v[214:217], v143 offset:1024
	ds_read_b128 v[218:221], v143 offset:2048
	ds_read_b128 v[222:225], v143 offset:3072
	ds_read_b128 v[226:229], v143 offset:4096
	ds_read_b128 v[230:233], v143 offset:5120
	ds_read_b128 v[234:237], v143 offset:6144
	ds_read_b128 v[238:241], v143 offset:7168
	global_load_lds_dwordx4 v[162:163], off
	v_lshl_add_u64 v[162:163], s[22:23], 0, v[138:139]
	s_add_i32 m0, s27, 0xe000
	s_nop 0
	global_load_lds_dwordx4 v[162:163], off
	s_waitcnt vmcnt(24)
	s_waitcnt lgkmcnt(0)
	s_barrier
	s_setprio 1
	s_waitcnt lgkmcnt(0)
	v_mfma_f32_16x16x32_bf16 v[126:129], v[144:147], v[210:213], v[126:129]
	v_mfma_f32_16x16x32_bf16 v[122:125], v[172:175], v[210:213], v[122:125]
	v_mfma_f32_16x16x32_bf16 v[118:121], v[144:147], v[218:221], v[118:121]
	v_mfma_f32_16x16x32_bf16 v[114:117], v[172:175], v[218:221], v[114:117]
	v_mfma_f32_16x16x32_bf16 v[110:113], v[144:147], v[226:229], v[110:113]
	v_mfma_f32_16x16x32_bf16 v[106:109], v[172:175], v[226:229], v[106:109]
	v_mfma_f32_16x16x32_bf16 v[102:105], v[144:147], v[234:237], v[102:105]
	v_mfma_f32_16x16x32_bf16 v[98:101], v[172:175], v[234:237], v[98:101]
	v_mfma_f32_16x16x32_bf16 v[126:129], v[148:151], v[214:217], v[126:129]
	v_mfma_f32_16x16x32_bf16 v[122:125], v[190:193], v[214:217], v[122:125]
	v_mfma_f32_16x16x32_bf16 v[118:121], v[148:151], v[222:225], v[118:121]
	v_mfma_f32_16x16x32_bf16 v[114:117], v[190:193], v[222:225], v[114:117]
	v_mfma_f32_16x16x32_bf16 v[110:113], v[148:151], v[230:233], v[110:113]
	v_mfma_f32_16x16x32_bf16 v[106:109], v[190:193], v[230:233], v[106:109]
	v_mfma_f32_16x16x32_bf16 v[102:105], v[148:151], v[238:241], v[102:105]
	v_mfma_f32_16x16x32_bf16 v[98:101], v[190:193], v[238:241], v[98:101]
	s_setprio 0
	s_setprio 1
	v_mfma_f32_16x16x32_bf16 v[66:69], v[194:197], v[210:213], v[66:69]
	v_mfma_f32_16x16x32_bf16 v[58:61], v[202:205], v[210:213], v[58:61]
	v_mfma_f32_16x16x32_bf16 v[54:57], v[194:197], v[218:221], v[54:57]
	v_mfma_f32_16x16x32_bf16 v[50:53], v[202:205], v[218:221], v[50:53]
	v_mfma_f32_16x16x32_bf16 v[46:49], v[194:197], v[226:229], v[46:49]
	v_mfma_f32_16x16x32_bf16 v[42:45], v[202:205], v[226:229], v[42:45]
	v_mfma_f32_16x16x32_bf16 v[38:41], v[194:197], v[234:237], v[38:41]
	v_mfma_f32_16x16x32_bf16 v[34:37], v[202:205], v[234:237], v[34:37]
	v_mfma_f32_16x16x32_bf16 v[66:69], v[198:201], v[214:217], v[66:69]
	v_mfma_f32_16x16x32_bf16 v[58:61], v[206:209], v[214:217], v[58:61]
	v_mfma_f32_16x16x32_bf16 v[54:57], v[198:201], v[222:225], v[54:57]
	v_mfma_f32_16x16x32_bf16 v[50:53], v[206:209], v[222:225], v[50:53]
	v_mfma_f32_16x16x32_bf16 v[46:49], v[198:201], v[230:233], v[46:49]
	v_mfma_f32_16x16x32_bf16 v[42:45], v[206:209], v[230:233], v[42:45]
	v_mfma_f32_16x16x32_bf16 v[38:41], v[198:201], v[238:241], v[38:41]
	v_mfma_f32_16x16x32_bf16 v[34:37], v[206:209], v[238:241], v[34:37]
	s_setprio 0
	s_barrier
	s_add_i32 s3, s3, s26
	v_lshl_add_u64 v[162:163], s[0:1], 0, v[4:5]
	s_mov_b32 m0, s3
	ds_read_b128 v[210:213], v143 offset:16384
	ds_read_b128 v[214:217], v143 offset:17408
	ds_read_b128 v[218:221], v143 offset:18432
	ds_read_b128 v[222:225], v143 offset:19456
	ds_read_b128 v[226:229], v143 offset:20480
	ds_read_b128 v[230:233], v143 offset:21504
	ds_read_b128 v[234:237], v143 offset:22528
	ds_read_b128 v[238:241], v143 offset:23552
	global_load_lds_dwordx4 v[162:163], off
	s_add_i32 m0, s3, 0x2000
	s_add_u32 s4, s0, 0x80000
	v_lshl_add_u64 v[166:167], s[0:1], 0, v[130:131]
	s_addc_u32 s5, s1, 0
	s_add_i32 s3, s6, s26
	global_load_lds_dwordx4 v[166:167], off
	v_lshl_add_u64 v[176:177], s[4:5], 0, v[4:5]
	s_mov_b32 m0, s3
	v_lshl_add_u64 v[242:243], s[14:15], 0, v[132:133]
	global_load_lds_dwordx4 v[176:177], off
	v_lshl_add_u64 v[176:177], s[4:5], 0, v[130:131]
	s_add_i32 m0, s3, 0x2000
	s_nop 0
	global_load_lds_dwordx4 v[176:177], off
	v_lshl_add_u64 v[176:177], s[14:15], 0, v[134:135]
	s_mov_b32 m0, s27
	s_nop 0
	global_load_lds_dwordx4 v[176:177], off
	s_mov_b32 m0, s30
	s_nop 0
	global_load_lds_dwordx4 v[242:243], off
	s_waitcnt vmcnt(24)
	s_waitcnt lgkmcnt(0)
	s_barrier
	s_setprio 1
	s_waitcnt lgkmcnt(0)
	v_mfma_f32_16x16x32_bf16 v[94:97], v[144:147], v[210:213], v[94:97]
	v_mfma_f32_16x16x32_bf16 v[90:93], v[172:175], v[210:213], v[90:93]
	v_mfma_f32_16x16x32_bf16 v[86:89], v[144:147], v[218:221], v[86:89]
	v_mfma_f32_16x16x32_bf16 v[82:85], v[172:175], v[218:221], v[82:85]
	v_mfma_f32_16x16x32_bf16 v[78:81], v[144:147], v[226:229], v[78:81]
	v_mfma_f32_16x16x32_bf16 v[74:77], v[172:175], v[226:229], v[74:77]
	v_mfma_f32_16x16x32_bf16 v[70:73], v[144:147], v[234:237], v[70:73]
	v_mfma_f32_16x16x32_bf16 v[62:65], v[172:175], v[234:237], v[62:65]
	v_mfma_f32_16x16x32_bf16 v[94:97], v[148:151], v[214:217], v[94:97]
	v_mfma_f32_16x16x32_bf16 v[90:93], v[190:193], v[214:217], v[90:93]
	v_mfma_f32_16x16x32_bf16 v[86:89], v[148:151], v[222:225], v[86:89]
	v_mfma_f32_16x16x32_bf16 v[82:85], v[190:193], v[222:225], v[82:85]
	v_mfma_f32_16x16x32_bf16 v[78:81], v[148:151], v[230:233], v[78:81]
	v_mfma_f32_16x16x32_bf16 v[74:77], v[190:193], v[230:233], v[74:77]
	v_mfma_f32_16x16x32_bf16 v[70:73], v[148:151], v[238:241], v[70:73]
	v_mfma_f32_16x16x32_bf16 v[62:65], v[190:193], v[238:241], v[62:65]
	s_setprio 0
	s_setprio 1
	v_mfma_f32_16x16x32_bf16 v[30:33], v[194:197], v[210:213], v[30:33]
	v_mfma_f32_16x16x32_bf16 v[26:29], v[202:205], v[210:213], v[26:29]
	v_mfma_f32_16x16x32_bf16 v[22:25], v[194:197], v[218:221], v[22:25]
	v_mfma_f32_16x16x32_bf16 v[18:21], v[202:205], v[218:221], v[18:21]
	v_mfma_f32_16x16x32_bf16 v[14:17], v[194:197], v[226:229], v[14:17]
	v_mfma_f32_16x16x32_bf16 v[10:13], v[202:205], v[226:229], v[10:13]
	v_mfma_f32_16x16x32_bf16 v[6:9], v[194:197], v[234:237], v[6:9]
	v_mfma_f32_16x16x32_bf16 v[0:3], v[202:205], v[234:237], v[0:3]
	v_mfma_f32_16x16x32_bf16 v[30:33], v[198:201], v[214:217], v[30:33]
	v_mfma_f32_16x16x32_bf16 v[26:29], v[206:209], v[214:217], v[26:29]
	v_mfma_f32_16x16x32_bf16 v[22:25], v[198:201], v[222:225], v[22:25]
	v_mfma_f32_16x16x32_bf16 v[18:21], v[206:209], v[222:225], v[18:21]
	v_mfma_f32_16x16x32_bf16 v[14:17], v[198:201], v[230:233], v[14:17]
	v_mfma_f32_16x16x32_bf16 v[10:13], v[206:209], v[230:233], v[10:13]
	v_mfma_f32_16x16x32_bf16 v[6:9], v[198:201], v[238:241], v[6:9]
	v_mfma_f32_16x16x32_bf16 v[0:3], v[206:209], v[238:241], v[0:3]
	s_setprio 0
	s_barrier
	s_branch .Lpeelmid_252

.Lpeelmid_252:
	s_add_i32 s3, 0, 0x18000
	v_add_u32_e32 v164, s3, v141
	s_add_i32 s6, 0, 0x1c000
	ds_read_b128 v[144:147], v164
	ds_read_b128 v[148:151], v164 offset:1024
	ds_read_b128 v[172:175], v164 offset:2048
	ds_read_b128 v[190:193], v164 offset:3072
	v_add_u32_e32 v164, s6, v141
	ds_read_b128 v[194:197], v164
	ds_read_b128 v[198:201], v164 offset:1024
	ds_read_b128 v[202:205], v164 offset:2048
	ds_read_b128 v[206:209], v164 offset:3072
	s_add_u32 s4, s14, 0x80000
	s_addc_u32 s5, s15, 0
	s_mov_b32 m0, s31
	v_lshl_add_u64 v[244:245], s[4:5], 0, v[134:135]
	ds_read_b128 v[210:213], v143 offset:32768
	ds_read_b128 v[214:217], v143 offset:33792
	ds_read_b128 v[218:221], v143 offset:34816
	ds_read_b128 v[222:225], v143 offset:35840
	ds_read_b128 v[226:229], v143 offset:36864
	ds_read_b128 v[230:233], v143 offset:37888
	ds_read_b128 v[234:237], v143 offset:38912
	ds_read_b128 v[238:241], v143 offset:39936
	global_load_lds_dwordx4 v[244:245], off
	v_lshl_add_u64 v[244:245], s[4:5], 0, v[132:133]
	s_mov_b32 m0, s34
	s_nop 0
	global_load_lds_dwordx4 v[244:245], off
	s_waitcnt vmcnt(8)
	s_waitcnt lgkmcnt(0)
	s_barrier
	s_setprio 1
	s_waitcnt lgkmcnt(0)
	v_mfma_f32_16x16x32_bf16 v[126:129], v[144:147], v[210:213], v[126:129]
	v_mfma_f32_16x16x32_bf16 v[122:125], v[172:175], v[210:213], v[122:125]
	v_mfma_f32_16x16x32_bf16 v[118:121], v[144:147], v[218:221], v[118:121]
	v_mfma_f32_16x16x32_bf16 v[114:117], v[172:175], v[218:221], v[114:117]
	v_mfma_f32_16x16x32_bf16 v[110:113], v[144:147], v[226:229], v[110:113]
	v_mfma_f32_16x16x32_bf16 v[106:109], v[172:175], v[226:229], v[106:109]
	v_mfma_f32_16x16x32_bf16 v[102:105], v[144:147], v[234:237], v[102:105]
	v_mfma_f32_16x16x32_bf16 v[98:101], v[172:175], v[234:237], v[98:101]
	v_mfma_f32_16x16x32_bf16 v[126:129], v[148:151], v[214:217], v[126:129]
	v_mfma_f32_16x16x32_bf16 v[122:125], v[190:193], v[214:217], v[122:125]
	v_mfma_f32_16x16x32_bf16 v[118:121], v[148:151], v[222:225], v[118:121]
	v_mfma_f32_16x16x32_bf16 v[114:117], v[190:193], v[222:225], v[114:117]
	v_mfma_f32_16x16x32_bf16 v[110:113], v[148:151], v[230:233], v[110:113]
	v_mfma_f32_16x16x32_bf16 v[106:109], v[190:193], v[230:233], v[106:109]
	v_mfma_f32_16x16x32_bf16 v[102:105], v[148:151], v[238:241], v[102:105]
	v_mfma_f32_16x16x32_bf16 v[98:101], v[190:193], v[238:241], v[98:101]
	s_setprio 0
	s_setprio 1
	v_mfma_f32_16x16x32_bf16 v[66:69], v[194:197], v[210:213], v[66:69]
	v_mfma_f32_16x16x32_bf16 v[58:61], v[202:205], v[210:213], v[58:61]
	v_mfma_f32_16x16x32_bf16 v[54:57], v[194:197], v[218:221], v[54:57]
	v_mfma_f32_16x16x32_bf16 v[50:53], v[202:205], v[218:221], v[50:53]
	v_mfma_f32_16x16x32_bf16 v[46:49], v[194:197], v[226:229], v[46:49]
	v_mfma_f32_16x16x32_bf16 v[42:45], v[202:205], v[226:229], v[42:45]
	v_mfma_f32_16x16x32_bf16 v[38:41], v[194:197], v[234:237], v[38:41]
	v_mfma_f32_16x16x32_bf16 v[34:37], v[202:205], v[234:237], v[34:37]
	v_mfma_f32_16x16x32_bf16 v[66:69], v[198:201], v[214:217], v[66:69]
	v_mfma_f32_16x16x32_bf16 v[58:61], v[206:209], v[214:217], v[58:61]
	v_mfma_f32_16x16x32_bf16 v[54:57], v[198:201], v[222:225], v[54:57]
	v_mfma_f32_16x16x32_bf16 v[50:53], v[206:209], v[222:225], v[50:53]
	v_mfma_f32_16x16x32_bf16 v[46:49], v[198:201], v[230:233], v[46:49]
	v_mfma_f32_16x16x32_bf16 v[42:45], v[206:209], v[230:233], v[42:45]
	v_mfma_f32_16x16x32_bf16 v[38:41], v[198:201], v[238:241], v[38:41]
	v_mfma_f32_16x16x32_bf16 v[34:37], v[206:209], v[238:241], v[34:37]
	s_setprio 0
	s_barrier
	s_add_i32 s3, s3, s26
	v_lshl_add_u64 v[162:163], v[162:163], 0, s[70:71]
	s_mov_b32 m0, s3
	ds_read_b128 v[210:213], v143 offset:49152
	ds_read_b128 v[214:217], v143 offset:50176
	ds_read_b128 v[218:221], v143 offset:51200
	ds_read_b128 v[222:225], v143 offset:52224
	ds_read_b128 v[226:229], v143 offset:53248
	ds_read_b128 v[230:233], v143 offset:54272
	ds_read_b128 v[234:237], v143 offset:55296
	ds_read_b128 v[238:241], v143 offset:56320
	global_load_lds_dwordx4 v[162:163], off
	s_add_i32 m0, s3, 0x2000
	s_add_u32 s0, s0, 0x80080
	v_lshl_add_u64 v[162:163], v[166:167], 0, s[70:71]
	s_addc_u32 s1, s1, 0
	s_add_i32 s3, s6, s26
	global_load_lds_dwordx4 v[162:163], off
	v_lshl_add_u64 v[162:163], s[0:1], 0, v[4:5]
	s_mov_b32 m0, s3
	s_nop 0
	global_load_lds_dwordx4 v[162:163], off
	v_lshl_add_u64 v[162:163], s[0:1], 0, v[130:131]
	s_add_i32 m0, s3, 0x2000
	s_nop 0
	global_load_lds_dwordx4 v[162:163], off
	v_lshl_add_u64 v[162:163], v[176:177], 0, s[70:71]
	s_mov_b32 m0, s35
	s_nop 0
	global_load_lds_dwordx4 v[162:163], off
	v_lshl_add_u64 v[162:163], v[242:243], 0, s[70:71]
	s_mov_b32 m0, s36
	s_nop 0
	global_load_lds_dwordx4 v[162:163], off
	s_waitcnt vmcnt(8)
	s_waitcnt lgkmcnt(0)
	s_barrier
	s_setprio 1
	s_waitcnt lgkmcnt(0)
	v_mfma_f32_16x16x32_bf16 v[94:97], v[144:147], v[210:213], v[94:97]
	v_mfma_f32_16x16x32_bf16 v[90:93], v[172:175], v[210:213], v[90:93]
	v_mfma_f32_16x16x32_bf16 v[86:89], v[144:147], v[218:221], v[86:89]
	v_mfma_f32_16x16x32_bf16 v[82:85], v[172:175], v[218:221], v[82:85]
	v_mfma_f32_16x16x32_bf16 v[78:81], v[144:147], v[226:229], v[78:81]
	v_mfma_f32_16x16x32_bf16 v[74:77], v[172:175], v[226:229], v[74:77]
	v_mfma_f32_16x16x32_bf16 v[70:73], v[144:147], v[234:237], v[70:73]
	v_mfma_f32_16x16x32_bf16 v[62:65], v[172:175], v[234:237], v[62:65]
	v_mfma_f32_16x16x32_bf16 v[94:97], v[148:151], v[214:217], v[94:97]
	v_mfma_f32_16x16x32_bf16 v[90:93], v[190:193], v[214:217], v[90:93]
	v_mfma_f32_16x16x32_bf16 v[86:89], v[148:151], v[222:225], v[86:89]
	v_mfma_f32_16x16x32_bf16 v[82:85], v[190:193], v[222:225], v[82:85]
	v_mfma_f32_16x16x32_bf16 v[78:81], v[148:151], v[230:233], v[78:81]
	v_mfma_f32_16x16x32_bf16 v[74:77], v[190:193], v[230:233], v[74:77]
	v_mfma_f32_16x16x32_bf16 v[70:73], v[148:151], v[238:241], v[70:73]
	v_mfma_f32_16x16x32_bf16 v[62:65], v[190:193], v[238:241], v[62:65]
	s_setprio 0
	s_setprio 1
	v_mfma_f32_16x16x32_bf16 v[30:33], v[194:197], v[210:213], v[30:33]
	v_mfma_f32_16x16x32_bf16 v[26:29], v[202:205], v[210:213], v[26:29]
	v_mfma_f32_16x16x32_bf16 v[22:25], v[194:197], v[218:221], v[22:25]
	v_mfma_f32_16x16x32_bf16 v[18:21], v[202:205], v[218:221], v[18:21]
	v_mfma_f32_16x16x32_bf16 v[14:17], v[194:197], v[226:229], v[14:17]
	v_mfma_f32_16x16x32_bf16 v[10:13], v[202:205], v[226:229], v[10:13]
	v_mfma_f32_16x16x32_bf16 v[6:9], v[194:197], v[234:237], v[6:9]
	v_mfma_f32_16x16x32_bf16 v[0:3], v[202:205], v[234:237], v[0:3]
	v_mfma_f32_16x16x32_bf16 v[30:33], v[198:201], v[214:217], v[30:33]
	v_mfma_f32_16x16x32_bf16 v[26:29], v[206:209], v[214:217], v[26:29]
	v_mfma_f32_16x16x32_bf16 v[22:25], v[198:201], v[222:225], v[22:25]
	v_mfma_f32_16x16x32_bf16 v[18:21], v[206:209], v[222:225], v[18:21]
	v_mfma_f32_16x16x32_bf16 v[14:17], v[198:201], v[230:233], v[14:17]
	v_mfma_f32_16x16x32_bf16 v[10:13], v[206:209], v[230:233], v[10:13]
	v_mfma_f32_16x16x32_bf16 v[6:9], v[198:201], v[238:241], v[6:9]
	v_mfma_f32_16x16x32_bf16 v[0:3], v[206:209], v[238:241], v[0:3]
	s_setprio 0
	s_barrier
	s_add_i32 s24, s24, 2
	s_add_u32 s22, s22, 0x100
	s_addc_u32 s23, s23, 0
	s_add_u32 s9, s9, 0x100
	s_addc_u32 s10, s10, 0
	s_cmp_gt_u32 s24, 29
	s_cbranch_scc0 .LBB0_252
	s_and_b64 vcc, exec, s[44:45]
	s_cbranch_vccz .LBB0_255
	s_barrier

.LBB0_851:
	s_ashr_i32 s3, s37, 24
	s_lshl_b32 s2, s37, 8
	s_andn2_b32 s3, s3, 63
	s_add_i32 s2, s3, s2
	s_ashr_i32 s3, s2, 31
	s_lshl_b64 s[2:3], s[2:3], 12
	v_readlane_b32 s4, v252, 6
	v_readlane_b32 s5, v252, 7
	s_add_u32 s76, s4, s2
	s_addc_u32 s77, s5, s3
	s_and_b64 s[2:3], s[38:39], exec
	s_cselect_b32 s2, s77, s15
	s_cselect_b32 s8, s76, s14
	s_ashr_i32 s59, s58, 31
	s_lshl_b64 s[4:5], s[58:59], 20
	v_readlane_b32 s6, v252, 4
	v_readlane_b32 s7, v252, 5
	s_add_u32 s78, s6, s4
	s_addc_u32 s79, s7, s5
	s_and_b64 s[4:5], s[38:39], exec
	s_cselect_b32 s10, s79, s1
	s_cselect_b32 s24, s78, s0
	s_add_u32 s22, s14, 0x80080
	s_addc_u32 s23, s15, 0
	s_add_u32 s9, s0, 0x100
	v_mov_b32_e32 v0, 0
	s_addc_u32 s25, s1, 0
	s_mov_b32 s28, -2
	v_mov_b32_e32 v1, v0
	v_mov_b32_e32 v2, v0
	v_mov_b32_e32 v3, v0
	v_mov_b32_e32 v6, v0
	v_mov_b32_e32 v7, v0
	v_mov_b32_e32 v8, v0
	v_mov_b32_e32 v9, v0
	v_mov_b32_e32 v10, v0
	v_mov_b32_e32 v11, v0
	v_mov_b32_e32 v12, v0
	v_mov_b32_e32 v13, v0
	v_mov_b32_e32 v14, v0
	v_mov_b32_e32 v15, v0
	v_mov_b32_e32 v16, v0
	v_mov_b32_e32 v17, v0
	v_mov_b32_e32 v18, v0
	v_mov_b32_e32 v19, v0
	v_mov_b32_e32 v20, v0
	v_mov_b32_e32 v21, v0
	v_mov_b32_e32 v22, v0
	v_mov_b32_e32 v23, v0
	v_mov_b32_e32 v24, v0
	v_mov_b32_e32 v25, v0
	v_mov_b32_e32 v26, v0
	v_mov_b32_e32 v27, v0
	v_mov_b32_e32 v28, v0
	v_mov_b32_e32 v29, v0
	v_mov_b32_e32 v30, v0
	v_mov_b32_e32 v31, v0
	v_mov_b32_e32 v32, v0
	v_mov_b32_e32 v33, v0
	v_mov_b32_e32 v66, v0
	v_mov_b32_e32 v67, v0
	v_mov_b32_e32 v68, v0
	v_mov_b32_e32 v69, v0
	v_mov_b32_e32 v70, v0
	v_mov_b32_e32 v71, v0
	v_mov_b32_e32 v72, v0
	v_mov_b32_e32 v73, v0
	v_mov_b32_e32 v74, v0
	v_mov_b32_e32 v75, v0
	v_mov_b32_e32 v76, v0
	v_mov_b32_e32 v77, v0
	v_mov_b32_e32 v78, v0
	v_mov_b32_e32 v79, v0
	v_mov_b32_e32 v80, v0
	v_mov_b32_e32 v81, v0
	v_mov_b32_e32 v82, v0
	v_mov_b32_e32 v83, v0
	v_mov_b32_e32 v84, v0
	v_mov_b32_e32 v85, v0
	v_mov_b32_e32 v86, v0
	v_mov_b32_e32 v87, v0
	v_mov_b32_e32 v88, v0
	v_mov_b32_e32 v89, v0
	v_mov_b32_e32 v90, v0
	v_mov_b32_e32 v91, v0
	v_mov_b32_e32 v92, v0
	v_mov_b32_e32 v93, v0
	v_mov_b32_e32 v94, v0
	v_mov_b32_e32 v95, v0
	v_mov_b32_e32 v96, v0
	v_mov_b32_e32 v97, v0
	v_mov_b32_e32 v34, v0
	v_mov_b32_e32 v35, v0
	v_mov_b32_e32 v36, v0
	v_mov_b32_e32 v37, v0
	v_mov_b32_e32 v38, v0
	v_mov_b32_e32 v39, v0
	v_mov_b32_e32 v40, v0
	v_mov_b32_e32 v41, v0
	v_mov_b32_e32 v42, v0
	v_mov_b32_e32 v43, v0
	v_mov_b32_e32 v44, v0
	v_mov_b32_e32 v45, v0
	v_mov_b32_e32 v46, v0
	v_mov_b32_e32 v47, v0
	v_mov_b32_e32 v48, v0
	v_mov_b32_e32 v49, v0
	v_mov_b32_e32 v50, v0
	v_mov_b32_e32 v51, v0
	v_mov_b32_e32 v52, v0
	v_mov_b32_e32 v53, v0
	v_mov_b32_e32 v54, v0
	v_mov_b32_e32 v55, v0
	v_mov_b32_e32 v56, v0
	v_mov_b32_e32 v57, v0
	v_mov_b32_e32 v58, v0
	v_mov_b32_e32 v59, v0
	v_mov_b32_e32 v60, v0
	v_mov_b32_e32 v61, v0
	v_mov_b32_e32 v62, v0
	v_mov_b32_e32 v63, v0
	v_mov_b32_e32 v64, v0
	v_mov_b32_e32 v65, v0
	v_mov_b32_e32 v98, v0
	v_mov_b32_e32 v99, v0
	v_mov_b32_e32 v100, v0
	v_mov_b32_e32 v101, v0
	v_mov_b32_e32 v102, v0
	v_mov_b32_e32 v103, v0
	v_mov_b32_e32 v104, v0
	v_mov_b32_e32 v105, v0
	v_mov_b32_e32 v106, v0
	v_mov_b32_e32 v107, v0
	v_mov_b32_e32 v108, v0
	v_mov_b32_e32 v109, v0
	v_mov_b32_e32 v110, v0
	v_mov_b32_e32 v111, v0
	v_mov_b32_e32 v112, v0
	v_mov_b32_e32 v113, v0
	v_mov_b32_e32 v114, v0
	v_mov_b32_e32 v115, v0
	v_mov_b32_e32 v116, v0
	v_mov_b32_e32 v117, v0
	v_mov_b32_e32 v118, v0
	v_mov_b32_e32 v119, v0
	v_mov_b32_e32 v120, v0
	v_mov_b32_e32 v121, v0
	v_mov_b32_e32 v122, v0
	v_mov_b32_e32 v123, v0
	v_mov_b32_e32 v124, v0
	v_mov_b32_e32 v125, v0
	v_mov_b32_e32 v126, v0
	v_mov_b32_e32 v127, v0
	v_mov_b32_e32 v128, v0
	v_mov_b32_e32 v129, v0
	s_cmp_eq_u32 s36, 1
	s_cbranch_scc1 .LBB0_852
	s_add_u32 s0, s22, 0xfff80080
	s_addc_u32 s1, s23, -1
	s_add_i32 s3, 0, 0x10000
	s_cmp_eq_u32 s28, 28
	s_cselect_b32 s15, s2, s1
	s_cselect_b32 s14, s8, s0
	v_add_u32_e32 v167, s3, v163
	s_cselect_b32 s1, s10, s25
	s_cselect_b32 s0, s24, s9
	s_add_i32 s6, 0, 0x14000
	ds_read_b128 v[140:143], v167
	ds_read_b128 v[144:147], v167 offset:1024
	ds_read_b128 v[148:151], v167 offset:2048
	ds_read_b128 v[172:175], v167 offset:3072
	v_add_u32_e32 v167, s6, v163
	ds_read_b128 v[190:193], v167
	ds_read_b128 v[194:197], v167 offset:1024
	ds_read_b128 v[198:201], v167 offset:2048
	ds_read_b128 v[202:205], v167 offset:3072
	v_lshl_add_u64 v[176:177], s[22:23], 0, v[136:137]
	s_add_i32 m0, s26, 0xc000
	ds_read_b128 v[206:209], v166
	ds_read_b128 v[210:213], v166 offset:1024
	ds_read_b128 v[214:217], v166 offset:2048
	ds_read_b128 v[218:221], v166 offset:3072
	ds_read_b128 v[222:225], v166 offset:4096
	ds_read_b128 v[226:229], v166 offset:5120
	ds_read_b128 v[230:233], v166 offset:6144
	ds_read_b128 v[234:237], v166 offset:7168
	global_load_lds_dwordx4 v[176:177], off
	v_lshl_add_u64 v[176:177], s[22:23], 0, v[138:139]
	s_add_i32 m0, s26, 0xe000
	s_nop 0
	global_load_lds_dwordx4 v[176:177], off
	s_waitcnt vmcnt(24)
	s_waitcnt lgkmcnt(0)
	s_barrier
	s_setprio 1
	s_waitcnt lgkmcnt(0)
	v_mfma_f32_16x16x32_bf16 v[126:129], v[140:143], v[206:209], v[126:129]
	v_mfma_f32_16x16x32_bf16 v[122:125], v[148:151], v[206:209], v[122:125]
	v_mfma_f32_16x16x32_bf16 v[118:121], v[140:143], v[214:217], v[118:121]
	v_mfma_f32_16x16x32_bf16 v[114:117], v[148:151], v[214:217], v[114:117]
	v_mfma_f32_16x16x32_bf16 v[110:113], v[140:143], v[222:225], v[110:113]
	v_mfma_f32_16x16x32_bf16 v[106:109], v[148:151], v[222:225], v[106:109]
	v_mfma_f32_16x16x32_bf16 v[102:105], v[140:143], v[230:233], v[102:105]
	v_mfma_f32_16x16x32_bf16 v[98:101], v[148:151], v[230:233], v[98:101]
	v_mfma_f32_16x16x32_bf16 v[126:129], v[144:147], v[210:213], v[126:129]
	v_mfma_f32_16x16x32_bf16 v[122:125], v[172:175], v[210:213], v[122:125]
	v_mfma_f32_16x16x32_bf16 v[118:121], v[144:147], v[218:221], v[118:121]
	v_mfma_f32_16x16x32_bf16 v[114:117], v[172:175], v[218:221], v[114:117]
	v_mfma_f32_16x16x32_bf16 v[110:113], v[144:147], v[226:229], v[110:113]
	v_mfma_f32_16x16x32_bf16 v[106:109], v[172:175], v[226:229], v[106:109]
	v_mfma_f32_16x16x32_bf16 v[102:105], v[144:147], v[234:237], v[102:105]
	v_mfma_f32_16x16x32_bf16 v[98:101], v[172:175], v[234:237], v[98:101]
	s_setprio 0
	s_setprio 1
	v_mfma_f32_16x16x32_bf16 v[62:65], v[190:193], v[206:209], v[62:65]
	v_mfma_f32_16x16x32_bf16 v[58:61], v[198:201], v[206:209], v[58:61]
	v_mfma_f32_16x16x32_bf16 v[54:57], v[190:193], v[214:217], v[54:57]
	v_mfma_f32_16x16x32_bf16 v[50:53], v[198:201], v[214:217], v[50:53]
	v_mfma_f32_16x16x32_bf16 v[46:49], v[190:193], v[222:225], v[46:49]
	v_mfma_f32_16x16x32_bf16 v[42:45], v[198:201], v[222:225], v[42:45]
	v_mfma_f32_16x16x32_bf16 v[38:41], v[190:193], v[230:233], v[38:41]
	v_mfma_f32_16x16x32_bf16 v[34:37], v[198:201], v[230:233], v[34:37]
	v_mfma_f32_16x16x32_bf16 v[62:65], v[194:197], v[210:213], v[62:65]
	v_mfma_f32_16x16x32_bf16 v[58:61], v[202:205], v[210:213], v[58:61]
	v_mfma_f32_16x16x32_bf16 v[54:57], v[194:197], v[218:221], v[54:57]
	v_mfma_f32_16x16x32_bf16 v[50:53], v[202:205], v[218:221], v[50:53]
	v_mfma_f32_16x16x32_bf16 v[46:49], v[194:197], v[226:229], v[46:49]
	v_mfma_f32_16x16x32_bf16 v[42:45], v[202:205], v[226:229], v[42:45]
	v_mfma_f32_16x16x32_bf16 v[38:41], v[194:197], v[234:237], v[38:41]
	v_mfma_f32_16x16x32_bf16 v[34:37], v[202:205], v[234:237], v[34:37]
	s_setprio 0
	s_barrier
	s_add_i32 s3, s3, s11
	v_lshl_add_u64 v[176:177], s[0:1], 0, v[4:5]
	s_mov_b32 m0, s3
	ds_read_b128 v[206:209], v166 offset:16384
	ds_read_b128 v[210:213], v166 offset:17408
	ds_read_b128 v[214:217], v166 offset:18432
	ds_read_b128 v[218:221], v166 offset:19456
	ds_read_b128 v[222:225], v166 offset:20480
	ds_read_b128 v[226:229], v166 offset:21504
	ds_read_b128 v[230:233], v166 offset:22528
	ds_read_b128 v[234:237], v166 offset:23552
	global_load_lds_dwordx4 v[176:177], off
	s_add_i32 m0, s3, 0x2000
	s_add_u32 s4, s0, 0x80000
	v_lshl_add_u64 v[238:239], s[0:1], 0, v[134:135]
	s_addc_u32 s5, s1, 0
	s_add_i32 s3, s6, s11
	global_load_lds_dwordx4 v[238:239], off
	v_lshl_add_u64 v[240:241], s[4:5], 0, v[4:5]
	s_mov_b32 m0, s3
	v_lshl_add_u64 v[242:243], s[14:15], 0, v[132:133]
	global_load_lds_dwordx4 v[240:241], off
	v_lshl_add_u64 v[240:241], s[4:5], 0, v[134:135]
	s_add_i32 m0, s3, 0x2000
	s_nop 0
	global_load_lds_dwordx4 v[240:241], off
	v_lshl_add_u64 v[240:241], s[14:15], 0, v[130:131]
	s_mov_b32 m0, s26
	s_nop 0
	global_load_lds_dwordx4 v[240:241], off
	s_mov_b32 m0, s27
	s_nop 0
	global_load_lds_dwordx4 v[242:243], off
	s_waitcnt vmcnt(24)
	s_waitcnt lgkmcnt(0)
	s_barrier
	s_setprio 1
	s_waitcnt lgkmcnt(0)
	v_mfma_f32_16x16x32_bf16 v[94:97], v[140:143], v[206:209], v[94:97]
	v_mfma_f32_16x16x32_bf16 v[90:93], v[148:151], v[206:209], v[90:93]
	v_mfma_f32_16x16x32_bf16 v[86:89], v[140:143], v[214:217], v[86:89]
	v_mfma_f32_16x16x32_bf16 v[82:85], v[148:151], v[214:217], v[82:85]
	v_mfma_f32_16x16x32_bf16 v[78:81], v[140:143], v[222:225], v[78:81]
	v_mfma_f32_16x16x32_bf16 v[74:77], v[148:151], v[222:225], v[74:77]
	v_mfma_f32_16x16x32_bf16 v[70:73], v[140:143], v[230:233], v[70:73]
	v_mfma_f32_16x16x32_bf16 v[66:69], v[148:151], v[230:233], v[66:69]
	v_mfma_f32_16x16x32_bf16 v[94:97], v[144:147], v[210:213], v[94:97]
	v_mfma_f32_16x16x32_bf16 v[90:93], v[172:175], v[210:213], v[90:93]
	v_mfma_f32_16x16x32_bf16 v[86:89], v[144:147], v[218:221], v[86:89]
	v_mfma_f32_16x16x32_bf16 v[82:85], v[172:175], v[218:221], v[82:85]
	v_mfma_f32_16x16x32_bf16 v[78:81], v[144:147], v[226:229], v[78:81]
	v_mfma_f32_16x16x32_bf16 v[74:77], v[172:175], v[226:229], v[74:77]
	v_mfma_f32_16x16x32_bf16 v[70:73], v[144:147], v[234:237], v[70:73]
	v_mfma_f32_16x16x32_bf16 v[66:69], v[172:175], v[234:237], v[66:69]
	s_setprio 0
	s_setprio 1
	v_mfma_f32_16x16x32_bf16 v[30:33], v[190:193], v[206:209], v[30:33]
	v_mfma_f32_16x16x32_bf16 v[26:29], v[198:201], v[206:209], v[26:29]
	v_mfma_f32_16x16x32_bf16 v[22:25], v[190:193], v[214:217], v[22:25]
	v_mfma_f32_16x16x32_bf16 v[18:21], v[198:201], v[214:217], v[18:21]
	v_mfma_f32_16x16x32_bf16 v[14:17], v[190:193], v[222:225], v[14:17]
	v_mfma_f32_16x16x32_bf16 v[10:13], v[198:201], v[222:225], v[10:13]
	v_mfma_f32_16x16x32_bf16 v[6:9], v[190:193], v[230:233], v[6:9]
	v_mfma_f32_16x16x32_bf16 v[0:3], v[198:201], v[230:233], v[0:3]
	v_mfma_f32_16x16x32_bf16 v[30:33], v[194:197], v[210:213], v[30:33]
	v_mfma_f32_16x16x32_bf16 v[26:29], v[202:205], v[210:213], v[26:29]
	v_mfma_f32_16x16x32_bf16 v[22:25], v[194:197], v[218:221], v[22:25]
	v_mfma_f32_16x16x32_bf16 v[18:21], v[202:205], v[218:221], v[18:21]
	v_mfma_f32_16x16x32_bf16 v[14:17], v[194:197], v[226:229], v[14:17]
	v_mfma_f32_16x16x32_bf16 v[10:13], v[202:205], v[226:229], v[10:13]
	v_mfma_f32_16x16x32_bf16 v[6:9], v[194:197], v[234:237], v[6:9]
	v_mfma_f32_16x16x32_bf16 v[0:3], v[202:205], v[234:237], v[0:3]
	s_setprio 0
	s_barrier
	s_branch .Lpeelmid_852

.Lpeelmid_852:
	s_add_i32 s3, 0, 0x18000
	v_add_u32_e32 v167, s3, v163
	s_add_i32 s6, 0, 0x1c000
	ds_read_b128 v[140:143], v167
	ds_read_b128 v[144:147], v167 offset:1024
	ds_read_b128 v[148:151], v167 offset:2048
	ds_read_b128 v[172:175], v167 offset:3072
	v_add_u32_e32 v167, s6, v163
	ds_read_b128 v[190:193], v167
	ds_read_b128 v[194:197], v167 offset:1024
	ds_read_b128 v[198:201], v167 offset:2048
	ds_read_b128 v[202:205], v167 offset:3072
	s_add_u32 s4, s14, 0x80000
	s_addc_u32 s5, s15, 0
	s_mov_b32 m0, s30
	v_lshl_add_u64 v[244:245], s[4:5], 0, v[130:131]
	ds_read_b128 v[206:209], v166 offset:32768
	ds_read_b128 v[210:213], v166 offset:33792
	ds_read_b128 v[214:217], v166 offset:34816
	ds_read_b128 v[218:221], v166 offset:35840
	ds_read_b128 v[222:225], v166 offset:36864
	ds_read_b128 v[226:229], v166 offset:37888
	ds_read_b128 v[230:233], v166 offset:38912
	ds_read_b128 v[234:237], v166 offset:39936
	global_load_lds_dwordx4 v[244:245], off
	v_lshl_add_u64 v[244:245], s[4:5], 0, v[132:133]
	s_mov_b32 m0, s31
	s_nop 0
	global_load_lds_dwordx4 v[244:245], off
	s_waitcnt vmcnt(8)
	s_waitcnt lgkmcnt(0)
	s_barrier
	s_setprio 1
	s_waitcnt lgkmcnt(0)
	v_mfma_f32_16x16x32_bf16 v[126:129], v[140:143], v[206:209], v[126:129]
	v_mfma_f32_16x16x32_bf16 v[122:125], v[148:151], v[206:209], v[122:125]
	v_mfma_f32_16x16x32_bf16 v[118:121], v[140:143], v[214:217], v[118:121]
	v_mfma_f32_16x16x32_bf16 v[114:117], v[148:151], v[214:217], v[114:117]
	v_mfma_f32_16x16x32_bf16 v[110:113], v[140:143], v[222:225], v[110:113]
	v_mfma_f32_16x16x32_bf16 v[106:109], v[148:151], v[222:225], v[106:109]
	v_mfma_f32_16x16x32_bf16 v[102:105], v[140:143], v[230:233], v[102:105]
	v_mfma_f32_16x16x32_bf16 v[98:101], v[148:151], v[230:233], v[98:101]
	v_mfma_f32_16x16x32_bf16 v[126:129], v[144:147], v[210:213], v[126:129]
	v_mfma_f32_16x16x32_bf16 v[122:125], v[172:175], v[210:213], v[122:125]
	v_mfma_f32_16x16x32_bf16 v[118:121], v[144:147], v[218:221], v[118:121]
	v_mfma_f32_16x16x32_bf16 v[114:117], v[172:175], v[218:221], v[114:117]
	v_mfma_f32_16x16x32_bf16 v[110:113], v[144:147], v[226:229], v[110:113]
	v_mfma_f32_16x16x32_bf16 v[106:109], v[172:175], v[226:229], v[106:109]
	v_mfma_f32_16x16x32_bf16 v[102:105], v[144:147], v[234:237], v[102:105]
	v_mfma_f32_16x16x32_bf16 v[98:101], v[172:175], v[234:237], v[98:101]
	s_setprio 0
	s_setprio 1
	v_mfma_f32_16x16x32_bf16 v[62:65], v[190:193], v[206:209], v[62:65]
	v_mfma_f32_16x16x32_bf16 v[58:61], v[198:201], v[206:209], v[58:61]
	v_mfma_f32_16x16x32_bf16 v[54:57], v[190:193], v[214:217], v[54:57]
	v_mfma_f32_16x16x32_bf16 v[50:53], v[198:201], v[214:217], v[50:53]
	v_mfma_f32_16x16x32_bf16 v[46:49], v[190:193], v[222:225], v[46:49]
	v_mfma_f32_16x16x32_bf16 v[42:45], v[198:201], v[222:225], v[42:45]
	v_mfma_f32_16x16x32_bf16 v[38:41], v[190:193], v[230:233], v[38:41]
	v_mfma_f32_16x16x32_bf16 v[34:37], v[198:201], v[230:233], v[34:37]
	v_mfma_f32_16x16x32_bf16 v[62:65], v[194:197], v[210:213], v[62:65]
	v_mfma_f32_16x16x32_bf16 v[58:61], v[202:205], v[210:213], v[58:61]
	v_mfma_f32_16x16x32_bf16 v[54:57], v[194:197], v[218:221], v[54:57]
	v_mfma_f32_16x16x32_bf16 v[50:53], v[202:205], v[218:221], v[50:53]
	v_mfma_f32_16x16x32_bf16 v[46:49], v[194:197], v[226:229], v[46:49]
	v_mfma_f32_16x16x32_bf16 v[42:45], v[202:205], v[226:229], v[42:45]
	v_mfma_f32_16x16x32_bf16 v[38:41], v[194:197], v[234:237], v[38:41]
	v_mfma_f32_16x16x32_bf16 v[34:37], v[202:205], v[234:237], v[34:37]
	s_setprio 0
	s_barrier
	s_add_i32 s3, s3, s11
	v_lshl_add_u64 v[176:177], v[176:177], 0, s[70:71]
	s_mov_b32 m0, s3
	ds_read_b128 v[206:209], v166 offset:49152
	ds_read_b128 v[210:213], v166 offset:50176
	ds_read_b128 v[214:217], v166 offset:51200
	ds_read_b128 v[218:221], v166 offset:52224
	ds_read_b128 v[222:225], v166 offset:53248
	ds_read_b128 v[226:229], v166 offset:54272
	ds_read_b128 v[230:233], v166 offset:55296
	ds_read_b128 v[234:237], v166 offset:56320
	global_load_lds_dwordx4 v[176:177], off
	s_add_i32 m0, s3, 0x2000
	s_add_u32 s0, s0, 0x80080
	v_lshl_add_u64 v[176:177], v[238:239], 0, s[70:71]
	s_addc_u32 s1, s1, 0
	s_add_i32 s3, s6, s11
	global_load_lds_dwordx4 v[176:177], off
	v_lshl_add_u64 v[176:177], s[0:1], 0, v[4:5]
	s_mov_b32 m0, s3
	s_nop 0
	global_load_lds_dwordx4 v[176:177], off
	v_lshl_add_u64 v[176:177], s[0:1], 0, v[134:135]
	s_add_i32 m0, s3, 0x2000
	s_nop 0
	global_load_lds_dwordx4 v[176:177], off
	v_lshl_add_u64 v[176:177], v[240:241], 0, s[70:71]
	s_mov_b32 m0, s34
	s_nop 0
	global_load_lds_dwordx4 v[176:177], off
	v_lshl_add_u64 v[176:177], v[242:243], 0, s[70:71]
	s_mov_b32 m0, s35
	s_nop 0
	global_load_lds_dwordx4 v[176:177], off
	s_waitcnt vmcnt(8)
	s_waitcnt lgkmcnt(0)
	s_barrier
	s_setprio 1
	s_waitcnt lgkmcnt(0)
	v_mfma_f32_16x16x32_bf16 v[94:97], v[140:143], v[206:209], v[94:97]
	v_mfma_f32_16x16x32_bf16 v[90:93], v[148:151], v[206:209], v[90:93]
	v_mfma_f32_16x16x32_bf16 v[86:89], v[140:143], v[214:217], v[86:89]
	v_mfma_f32_16x16x32_bf16 v[82:85], v[148:151], v[214:217], v[82:85]
	v_mfma_f32_16x16x32_bf16 v[78:81], v[140:143], v[222:225], v[78:81]
	v_mfma_f32_16x16x32_bf16 v[74:77], v[148:151], v[222:225], v[74:77]
	v_mfma_f32_16x16x32_bf16 v[70:73], v[140:143], v[230:233], v[70:73]
	v_mfma_f32_16x16x32_bf16 v[66:69], v[148:151], v[230:233], v[66:69]
	v_mfma_f32_16x16x32_bf16 v[94:97], v[144:147], v[210:213], v[94:97]
	v_mfma_f32_16x16x32_bf16 v[90:93], v[172:175], v[210:213], v[90:93]
	v_mfma_f32_16x16x32_bf16 v[86:89], v[144:147], v[218:221], v[86:89]
	v_mfma_f32_16x16x32_bf16 v[82:85], v[172:175], v[218:221], v[82:85]
	v_mfma_f32_16x16x32_bf16 v[78:81], v[144:147], v[226:229], v[78:81]
	v_mfma_f32_16x16x32_bf16 v[74:77], v[172:175], v[226:229], v[74:77]
	v_mfma_f32_16x16x32_bf16 v[70:73], v[144:147], v[234:237], v[70:73]
	v_mfma_f32_16x16x32_bf16 v[66:69], v[172:175], v[234:237], v[66:69]
	s_setprio 0
	s_setprio 1
	v_mfma_f32_16x16x32_bf16 v[30:33], v[190:193], v[206:209], v[30:33]
	v_mfma_f32_16x16x32_bf16 v[26:29], v[198:201], v[206:209], v[26:29]
	v_mfma_f32_16x16x32_bf16 v[22:25], v[190:193], v[214:217], v[22:25]
	v_mfma_f32_16x16x32_bf16 v[18:21], v[198:201], v[214:217], v[18:21]
	v_mfma_f32_16x16x32_bf16 v[14:17], v[190:193], v[222:225], v[14:17]
	v_mfma_f32_16x16x32_bf16 v[10:13], v[198:201], v[222:225], v[10:13]
	v_mfma_f32_16x16x32_bf16 v[6:9], v[190:193], v[230:233], v[6:9]
	v_mfma_f32_16x16x32_bf16 v[0:3], v[198:201], v[230:233], v[0:3]
	v_mfma_f32_16x16x32_bf16 v[30:33], v[194:197], v[210:213], v[30:33]
	v_mfma_f32_16x16x32_bf16 v[26:29], v[202:205], v[210:213], v[26:29]
	v_mfma_f32_16x16x32_bf16 v[22:25], v[194:197], v[218:221], v[22:25]
	v_mfma_f32_16x16x32_bf16 v[18:21], v[202:205], v[218:221], v[18:21]
	v_mfma_f32_16x16x32_bf16 v[14:17], v[194:197], v[226:229], v[14:17]
	v_mfma_f32_16x16x32_bf16 v[10:13], v[202:205], v[226:229], v[10:13]
	v_mfma_f32_16x16x32_bf16 v[6:9], v[194:197], v[234:237], v[6:9]
	v_mfma_f32_16x16x32_bf16 v[0:3], v[202:205], v[234:237], v[0:3]
	s_setprio 0
	s_barrier
	s_add_i32 s28, s28, 2
	s_add_u32 s22, s22, 0x100
	s_addc_u32 s23, s23, 0
	s_add_u32 s9, s9, 0x100
	s_addc_u32 s25, s25, 0
	s_cmp_gt_u32 s28, 29
	s_cbranch_scc0 .LBB0_852
	s_and_b64 vcc, exec, s[48:49]
	s_cbranch_vccz .LBB0_855
	s_barrier
